# up-projection epilogue: the 3-tap conv sum uses three v_fma instead of v_pk_mul + v_fma + two v_add (63 of 64 sites, one VALU instruction fewer each)
# speedup vs baseline: 1.0017x; 1.0017x over previous
; __device__ __forceinline__ unsigned cvt_pk_bf16(float lo, float hi) { unsigned r; asm volatile("v_cvt_pk_bf16_f32 %0, %1, %2" : "=v"(r) : "v"(lo), "v"(hi)); return r; }
;     __device__ __forceinline__ void operator()(const f32x4 (&acc)[2][2][4][2], const Unit& u, int wr, int wc, int fr, int fq) const {
;     ...
;                     const f32x4 g = acc[ai][1][m][n] * rs[ai][m], v = acc[ai][0][m][n] * rs[ai][m];
;                     f32x4 r1, r2, a;
; #pragma unroll
;                     for (int e = 0; e < 4; ++e) { r1[e] = __shfl(g[e], src1); r2[e] = __shfl(g[e], src2); }
; #pragma unroll
;                     for (int e = 0; e < 4; ++e) {
;                         const float p1 = fr >= 1 ? r1[e] : r1p[e], p2 = fr >= 2 ? r2[e] : r2p[e];
;                         const float gg = b4[e] + w0[e] * p2 + w1[e] * p1 + w2[e] * g[e];
;                         a[e] = gg * __builtin_amdgcn_rcpf(1.f + __expf(-gg)) * v[e];
;                     }
;                     r1p = r1; r2p = r2;
;                     const size_t row = (size_t)(u.pm * BM + ai * HALF + wr * 64 + m * 16 + fr);
;                     if (m == 0 && fr < 2) {
;                         *(f32x4*)(GF + (size_t)(slab * 2 + fr) * FF + cbase) = g; *(f32x4*)(VF + (size_t)(slab * 2 + fr) * FF + cbase) = v;
;                     } else {
;                         typedef unsigned u32x2v __attribute__((ext_vector_type(2)));
;                         u32x2v w; w.x = cvt_pk_bf16(a[0], a[1]); w.y = cvt_pk_bf16(a[2], a[3]);
;                         *(u32x2v*)(ACT + row * FF + cbase) = w;
.LBB0_41:
	v_lshl_add_u32 v160, s66, 8, v193
	v_ashrrev_i32_e32 v161, 31, v160
	v_mov_b32_e32 v148, v227
	v_bfe_u32 v205, v227, 4, 1
	v_mul_u32_u24_e32 v205, 24, v205
	s_and_b32 s98, s65, 1
	s_lshl_b32 s98, s98, 12
	s_add_i32 s98, s98, 0x20000
	s_add_i32 s99, s98, 0x800
	v_lshl_add_u32 v114, v193, 3, s98
	ds_read_b64 v[146:147], v114
	v_lshl_or_b32 v156, s64, 7, v198
	v_ashrrev_i32_e32 v157, 31, v156
	ds_read_b64 v[190:191], v114 offset:128
	ds_read_b64 v[188:189], v114 offset:256
	ds_read_b64 v[186:187], v114 offset:384
	ds_read_b64 v[176:177], v114 offset:1024
	ds_read_b64 v[174:175], v114 offset:1152
	ds_read_b64 v[172:173], v114 offset:1280
	ds_read_b64 v[170:171], v114 offset:1408
	v_lshlrev_b64 v[158:159], 2, v[156:157]
	v_lshl_add_u32 v166, v198, 2, s99
	v_lshl_add_u64 v[118:119], s[60:61], 0, v[158:159]
	v_lshl_add_u64 v[120:121], s[62:63], 0, v[158:159]
	v_lshl_add_u64 v[164:165], s[54:55], 0, v[158:159]
	ds_read_b128 v[114:117], v166
	ds_read_b128 v[138:141], v166 offset:512
	ds_read_b128 v[130:133], v166 offset:1024
	s_nop 0
	ds_read_b128 v[118:121], v166 offset:1536
	s_waitcnt lgkmcnt(0)
	v_ffbh_u32_e32 v149, v147
	v_min_u32_e32 v149, 32, v149
	v_lshlrev_b64 v[146:147], v149, v[146:147]
	v_min_u32_e32 v146, 1, v146
	v_or_b32_e32 v146, v147, v146
	v_cvt_f32_u32_e32 v146, v146
	v_sub_u32_e32 v149, 32, v149
	v_and_b32_e32 v147, 48, v148
	v_or3_b32 v148, v147, v195, v236
	v_ldexp_f32 v146, v146, v149
	v_fmamk_f32 v146, v146, 0x31000000, v232
	v_rsq_f32_e32 v162, v146
	v_or3_b32 v146, v147, v196, v236
	v_lshlrev_b32_e32 v200, 2, v146
	v_lshlrev_b32_e32 v161, 2, v148
	v_pk_mul_f32 v[146:147], v[134:135], v[162:163] op_sel_hi:[1,0]
	v_pk_mul_f32 v[148:149], v[136:137], v[162:163] op_sel_hi:[1,0]
	s_nop 1
	v_mov_b32_dpp v163, v146 row_ror:2 row_mask:0xf bank_mask:0xf
	v_mov_b32_dpp v179, v146 row_ror:1 row_mask:0xf bank_mask:0xf
	v_mov_b32_dpp v181, v147 row_ror:1 row_mask:0xf bank_mask:0xf
	v_mov_b32_dpp v201, v147 row_ror:2 row_mask:0xf bank_mask:0xf
	v_mov_b32_dpp v183, v148 row_ror:1 row_mask:0xf bank_mask:0xf
	v_mov_b32_dpp v202, v148 row_ror:2 row_mask:0xf bank_mask:0xf
	v_mov_b32_dpp v185, v149 row_ror:1 row_mask:0xf bank_mask:0xf
	v_mov_b32_dpp v203, v149 row_ror:2 row_mask:0xf bank_mask:0xf
	s_waitcnt lgkmcnt(7)
	v_pk_mul_f32 v[136:137], v[144:145], v[162:163] op_sel_hi:[1,0]
	v_pk_mul_f32 v[134:135], v[142:143], v[162:163] op_sel_hi:[1,0]
	s_and_saveexec_b64 s[10:11], s[42:43]
	s_xor_b64 s[10:11], exec, s[10:11]
	s_movk_i32 s17, 0x2b00
	s_movk_i32 s84, 0x300
	s_mov_b32 s86, 0x24000
	s_mov_b32 s88, 0x48800000
	s_cbranch_execz .LBB0_43
	v_mov_b32_e32 v142, v149
	v_mov_b32_e32 v143, v141
	v_mov_b32_e32 v184, v133
	s_waitcnt lgkmcnt(1)
	s_waitcnt lgkmcnt(0)
	v_fma_f32 v144, v117, v203, v121
	v_fma_f32 v143, v143, v185, v144
	v_fma_f32 v142, v142, v184, v143
	v_mul_f32_e32 v143, 0xbfb8aa3b, v142
	v_exp_f32_e32 v143, v143
	v_mov_b32_e32 v149, v140
	v_mov_b32_e32 v182, v132
	v_mov_b32_e32 v180, v131
	v_add_f32_e32 v143, 1.0, v143
	v_rcp_f32_e32 v143, v143
	v_mov_b32_e32 v178, v130
	v_mul_f32_e32 v142, v142, v143
	v_mul_f32_e32 v144, v137, v142
	v_fma_f32 v137, v116, v202, v120
	v_fma_f32 v137, v149, v183, v137
	v_fma_f32 v137, v148, v182, v137
	v_mul_f32_e32 v142, 0xbfb8aa3b, v137
	v_exp_f32_e32 v142, v142
	v_fma_f32 v143, v115, v201, v119
	v_add_f32_e32 v142, 1.0, v142
	v_rcp_f32_e32 v142, v142
	s_nop 0
	v_mul_f32_e32 v137, v137, v142
	v_mul_f32_e32 v142, v136, v137
	v_mov_b32_e32 v136, v147
	v_mov_b32_e32 v137, v139
	v_mov_b32_e32 v147, v138
	v_fma_f32 v137, v137, v181, v143
	v_fma_f32 v136, v136, v180, v137
	v_mul_f32_e32 v137, 0xbfb8aa3b, v136
	v_exp_f32_e32 v137, v137
	v_fma_f32 v143, v114, v163, v118
	v_add_f32_e32 v137, 1.0, v137
	v_rcp_f32_e32 v137, v137
	s_nop 0
	v_mul_f32_e32 v136, v136, v137
	v_mul_f32_e32 v135, v135, v136
	s_nop 0
	v_fma_f32 v137, v147, v179, v143
	v_fma_f32 v136, v146, v178, v137
	v_mul_f32_e32 v137, 0xbfb8aa3b, v136
	v_exp_f32_e32 v137, v137
	s_nop 0
	v_add_f32_e32 v137, 1.0, v137
	v_rcp_f32_e32 v137, v137
	s_nop 0
	v_mul_f32_e32 v136, v136, v137
	v_mul_f32_e32 v134, v134, v136
	v_mov_b64_e32 v[136:137], s[48:49]
	v_mad_i64_i32 v[136:137], s[12:13], v160, s17, v[136:137]
	v_cvt_pk_bf16_f32 v134, v134, v135
	v_cvt_pk_bf16_f32 v135, v142, v144
	v_lshl_add_u64 v[136:137], v[156:157], 1, v[136:137]
	v_mov_b32_e32 v220, v134
	v_mov_b32_e32 v221, v135

; __device__ __forceinline__ unsigned cvt_pk_bf16(float lo, float hi) { unsigned r; asm volatile("v_cvt_pk_bf16_f32 %0, %1, %2" : "=v"(r) : "v"(lo), "v"(hi)); return r; }
;     __device__ __forceinline__ void operator()(const f32x4 (&acc)[2][2][4][2], const Unit& u, int wr, int wc, int fr, int fq) const {
;     ...
;                     const f32x4 g = acc[ai][1][m][n] * rs[ai][m], v = acc[ai][0][m][n] * rs[ai][m];
;                     f32x4 r1, r2, a;
; #pragma unroll
;                     for (int e = 0; e < 4; ++e) { r1[e] = __shfl(g[e], src1); r2[e] = __shfl(g[e], src2); }
; #pragma unroll
;                     for (int e = 0; e < 4; ++e) {
;                         const float p1 = fr >= 1 ? r1[e] : r1p[e], p2 = fr >= 2 ? r2[e] : r2p[e];
;                         const float gg = b4[e] + w0[e] * p2 + w1[e] * p1 + w2[e] * g[e];
;                         a[e] = gg * __builtin_amdgcn_rcpf(1.f + __expf(-gg)) * v[e];
;                     }
;                     r1p = r1; r2p = r2;
;                     const size_t row = (size_t)(u.pm * BM + ai * HALF + wr * 64 + m * 16 + fr);
;                     if (m == 0 && fr < 2) {
;                         *(f32x4*)(GF + (size_t)(slab * 2 + fr) * FF + cbase) = g; *(f32x4*)(VF + (size_t)(slab * 2 + fr) * FF + cbase) = v;
;                     } else {
;                         typedef unsigned u32x2v __attribute__((ext_vector_type(2)));
;                         u32x2v w; w.x = cvt_pk_bf16(a[0], a[1]); w.y = cvt_pk_bf16(a[2], a[3]);
;                         *(u32x2v*)(ACT + row * FF + cbase) = w;
.Lalign_up:
	s_nop 0
	v_ffbh_u32_e32 v134, v191
	v_min_u32_e32 v136, 32, v134
	v_lshlrev_b64 v[134:135], v136, v[190:191]
	v_min_u32_e32 v134, 1, v134
	v_or_b32_e32 v134, v135, v134
	v_cvt_f32_u32_e32 v134, v134
	v_ffbh_u32_e32 v135, v189
	v_sub_u32_e32 v136, 32, v136
	v_min_u32_e32 v143, 32, v135
	v_ldexp_f32 v134, v134, v136
	v_fmamk_f32 v136, v134, 0x31000000, v232
	v_lshlrev_b64 v[134:135], v143, v[188:189]
	v_min_u32_e32 v134, 1, v134
	v_or_b32_e32 v134, v135, v134
	v_cvt_f32_u32_e32 v134, v134
	v_sub_u32_e32 v135, 32, v143
	v_rsq_f32_e32 v142, v136
	v_mov_b32_e32 v149, v141
	v_ldexp_f32 v134, v134, v135
	v_fmamk_f32 v136, v134, 0x31000000, v232
	v_ffbh_u32_e32 v134, v187
	v_min_u32_e32 v143, 32, v134
	v_lshlrev_b64 v[134:135], v143, v[186:187]
	v_min_u32_e32 v134, 1, v134
	v_or_b32_e32 v134, v135, v134
	v_cvt_f32_u32_e32 v134, v134
	v_sub_u32_e32 v143, 32, v143
	s_movk_i32 s10, 0x5600
	v_rsq_f32_e32 v136, v136
	v_ldexp_f32 v134, v134, v143
	v_add_u32_e32 v143, s12, v197
	v_pk_mul_f32 v[128:129], v[128:129], v[142:143] op_sel_hi:[1,0]
	s_nop 1
	v_mov_b32_dpp v186, v129 row_ror:1 row_mask:0xf bank_mask:0xf
	v_mov_b32_dpp v191, v129 row_ror:2 row_mask:0xf bank_mask:0xf
	v_mov_b32_e32 v148, v129
	v_pk_mul_f32 v[126:127], v[126:127], v[142:143] op_sel_hi:[1,0]
	v_mad_i64_i32 v[146:147], s[10:11], v143, s10, 0
	s_waitcnt lgkmcnt(1)
	v_cndmask_b32_e64 v185, v186, v185, s[40:41]
	s_waitcnt lgkmcnt(0)
	v_cndmask_b32_e64 v129, v203, v191, s[42:43]
	v_fma_f32 v129, v117, v129, v121
	v_fma_f32 v129, v149, v185, v129
	v_fma_f32 v148, v148, v184, v129
	v_mul_f32_e32 v129, 0xbfb8aa3b, v148
	v_exp_f32_e32 v129, v129
	v_mov_b32_dpp v149, v128 row_ror:1 row_mask:0xf bank_mask:0xf
	v_mov_b32_dpp v203, v128 row_ror:2 row_mask:0xf bank_mask:0xf
	v_mov_b32_dpp v143, v126 row_ror:1 row_mask:0xf bank_mask:0xf
	v_add_f32_e32 v129, 1.0, v129
	v_rcp_f32_e32 v185, v129
	s_waitcnt lgkmcnt(2)
	v_cndmask_b32_e64 v183, v149, v183, s[40:41]
	v_mov_b32_e32 v129, v140
	v_pk_mul_f32 v[128:129], v[128:129], v[182:183]
	s_waitcnt lgkmcnt(1)
	v_cndmask_b32_e64 v183, v202, v203, s[42:43]
	v_fma_f32 v183, v116, v183, v120
	v_add_f32_e32 v129, v129, v183
	v_add_f32_e32 v183, v128, v129
	v_mul_f32_e32 v128, 0xbfb8aa3b, v183
	v_mov_b32_dpp v189, v127 row_ror:1 row_mask:0xf bank_mask:0xf
	v_mov_b32_dpp v190, v127 row_ror:2 row_mask:0xf bank_mask:0xf
	v_exp_f32_e32 v128, v128
	s_waitcnt lgkmcnt(2)
	v_pk_mul_f32 v[124:125], v[124:125], v[142:143] op_sel_hi:[1,0]
	v_mul_f32_e32 v129, v148, v185
	v_mov_b32_dpp v187, v126 row_ror:2 row_mask:0xf bank_mask:0xf
	v_add_f32_e32 v128, 1.0, v128
	v_mul_f32_e32 v125, v125, v129
	v_rcp_f32_e32 v148, v128
	s_waitcnt lgkmcnt(2)
	v_cndmask_b32_e64 v181, v189, v181, s[40:41]
	v_mov_b32_e32 v128, v127
	v_mov_b32_e32 v129, v139
	s_waitcnt lgkmcnt(1)
	v_cndmask_b32_e64 v127, v201, v190, s[42:43]
	v_fma_f32 v127, v115, v127, v119
	v_fma_f32 v127, v129, v181, v127
	v_fma_f32 v128, v128, v180, v127
	v_mul_f32_e32 v127, 0xbfb8aa3b, v128
	v_exp_f32_e32 v129, v127
	v_cndmask_b32_e64 v179, v143, v179, s[40:41]
	v_mov_b32_e32 v127, v138
	s_waitcnt lgkmcnt(0)
	v_cndmask_b32_e64 v163, v163, v187, s[42:43]
	v_fma_f32 v163, v114, v163, v118
	v_fma_f32 v127, v127, v179, v163
	v_fma_f32 v126, v126, v178, v127
	v_mul_f32_e32 v127, 0xbfb8aa3b, v126
	v_exp_f32_e32 v127, v127
	v_add_f32_e32 v129, 1.0, v129
	v_rcp_f32_e32 v129, v129
	v_or_b32_e32 v137, 16, v160
	v_add_f32_e32 v127, 1.0, v127
	v_rcp_f32_e32 v127, v127
	v_mul_f32_e32 v148, v183, v148
	v_pk_mul_f32 v[112:113], v[112:113], v[136:137] op_sel_hi:[1,0]
	v_mul_f32_e32 v124, v124, v148
	s_nop 1
	v_mov_b32_dpp v148, v113 row_ror:1 row_mask:0xf bank_mask:0xf
	v_mov_b32_dpp v204, v113 row_ror:2 row_mask:0xf bank_mask:0xf
	v_pk_mul_f32 v[122:123], v[122:123], v[142:143] op_sel_hi:[1,0]
	v_mul_f32_e32 v128, v128, v129
	v_mul_f32_e32 v126, v126, v127
	v_mul_f32_e32 v123, v123, v128
	v_mul_f32_e32 v122, v122, v126
	v_mov_b64_e32 v[128:129], s[48:49]
	v_cvt_pk_bf16_f32 v126, v122, v123
	v_cvt_pk_bf16_f32 v127, v124, v125
	v_mad_i64_i32 v[122:123], s[10:11], v137, s17, v[128:129]
	v_lshlrev_b64 v[124:125], 1, v[156:157]
	v_lshl_add_u64 v[122:123], v[122:123], 0, v[124:125]
	v_mov_b32_e32 v206, v126
	v_mov_b32_e32 v207, v127
	s_waitcnt lgkmcnt(1)
	v_cndmask_b32_e64 v185, v148, v186, s[40:41]
	v_mov_b32_e32 v126, v113
	v_mov_b32_e32 v127, v141
	s_waitcnt lgkmcnt(0)
	v_cndmask_b32_e64 v113, v191, v204, s[42:43]
	v_fma_f32 v113, v117, v113, v121
	v_fma_f32 v113, v127, v185, v113
	v_fma_f32 v126, v126, v184, v113
	v_mul_f32_e32 v113, 0xbfb8aa3b, v126
	v_exp_f32_e32 v113, v113
	v_mov_b32_dpp v127, v112 row_ror:1 row_mask:0xf bank_mask:0xf
	v_mov_b32_dpp v186, v112 row_ror:2 row_mask:0xf bank_mask:0xf
	v_pk_mul_f32 v[110:111], v[110:111], v[136:137] op_sel_hi:[1,0]
	v_add_f32_e32 v113, 1.0, v113
	v_rcp_f32_e32 v179, v113
	s_waitcnt lgkmcnt(1)
	v_cndmask_b32_e64 v183, v127, v149, s[40:41]
	v_mov_b32_e32 v113, v140
	s_waitcnt lgkmcnt(0)
	v_cndmask_b32_e64 v149, v203, v186, s[42:43]
	v_fma_f32 v149, v116, v149, v120
	v_fma_f32 v113, v113, v183, v149
	v_fma_f32 v149, v112, v182, v113
	v_mov_b32_dpp v137, v110 row_ror:1 row_mask:0xf bank_mask:0xf
	v_mul_f32_e32 v112, 0xbfb8aa3b, v149
	v_mov_b32_dpp v201, v111 row_ror:1 row_mask:0xf bank_mask:0xf
	v_mov_b32_dpp v202, v111 row_ror:2 row_mask:0xf bank_mask:0xf
	v_exp_f32_e32 v112, v112
	s_waitcnt lgkmcnt(2)
	v_pk_mul_f32 v[108:109], v[108:109], v[136:137] op_sel_hi:[1,0]
	v_mul_f32_e32 v113, v126, v179
	v_mov_b32_dpp v163, v110 row_ror:2 row_mask:0xf bank_mask:0xf
	v_add_f32_e32 v112, 1.0, v112
	v_mul_f32_e32 v109, v109, v113
	v_rcp_f32_e32 v126, v112
	s_waitcnt lgkmcnt(2)
; __device__ __forceinline__ unsigned cvt_pk_bf16(float lo, float hi) { unsigned r; asm volatile("v_cvt_pk_bf16_f32 %0, %1, %2" : "=v"(r) : "v"(lo), "v"(hi)); return r; }
;     __device__ __forceinline__ void operator()(const f32x4 (&acc)[2][2][4][2], const Unit& u, int wr, int wc, int fr, int fq) const {
;     ...
;                     const f32x4 g = acc[ai][1][m][n] * rs[ai][m], v = acc[ai][0][m][n] * rs[ai][m];
;                     f32x4 r1, r2, a;
; #pragma unroll
;                     for (int e = 0; e < 4; ++e) { r1[e] = __shfl(g[e], src1); r2[e] = __shfl(g[e], src2); }
; #pragma unroll
;                     for (int e = 0; e < 4; ++e) {
;                         const float p1 = fr >= 1 ? r1[e] : r1p[e], p2 = fr >= 2 ? r2[e] : r2p[e];
;                         const float gg = b4[e] + w0[e] * p2 + w1[e] * p1 + w2[e] * g[e];
;                         a[e] = gg * __builtin_amdgcn_rcpf(1.f + __expf(-gg)) * v[e];
;                     }
;                     r1p = r1; r2p = r2;
;                     const size_t row = (size_t)(u.pm * BM + ai * HALF + wr * 64 + m * 16 + fr);
;                     if (m == 0 && fr < 2) {
;                         *(f32x4*)(GF + (size_t)(slab * 2 + fr) * FF + cbase) = g; *(f32x4*)(VF + (size_t)(slab * 2 + fr) * FF + cbase) = v;
;                     } else {
;                         typedef unsigned u32x2v __attribute__((ext_vector_type(2)));
;                         u32x2v w; w.x = cvt_pk_bf16(a[0], a[1]); w.y = cvt_pk_bf16(a[2], a[3]);
;                         *(u32x2v*)(ACT + row * FF + cbase) = w;
;                     }
;                     if (m == 3 && fr >= 14) *(f32x4*)(GL + (size_t)(slab * 2 + fr - 14) * FF + cbase) = g;
	v_cndmask_b32_e64 v181, v201, v189, s[40:41]
	v_mov_b32_e32 v112, v111
	v_mov_b32_e32 v113, v139
	s_waitcnt lgkmcnt(1)
	v_cndmask_b32_e64 v111, v190, v202, s[42:43]
	v_fma_f32 v111, v115, v111, v119
	v_fma_f32 v111, v113, v181, v111
	v_fma_f32 v112, v112, v180, v111
	v_mul_f32_e32 v111, 0xbfb8aa3b, v112
	v_exp_f32_e32 v113, v111
	v_cndmask_b32_e64 v179, v137, v143, s[40:41]
	v_mov_b32_e32 v111, v138
	s_waitcnt lgkmcnt(0)
	v_cndmask_b32_e64 v143, v187, v163, s[42:43]
	v_fma_f32 v143, v114, v143, v118
	v_fma_f32 v111, v111, v179, v143
	v_fma_f32 v110, v110, v178, v111
	v_mul_f32_e32 v111, 0xbfb8aa3b, v110
	v_exp_f32_e32 v111, v111
	v_add_f32_e32 v113, 1.0, v113
	v_rcp_f32_e32 v113, v113
	v_fmamk_f32 v134, v134, 0x31000000, v232
	v_add_f32_e32 v111, 1.0, v111
	v_rcp_f32_e32 v111, v111
	v_rsq_f32_e32 v134, v134
	v_pk_mul_f32 v[106:107], v[106:107], v[136:137] op_sel_hi:[1,0]
	v_mul_f32_e32 v126, v149, v126
	v_mul_f32_e32 v112, v112, v113
	v_mul_f32_e32 v110, v110, v111
	v_or_b32_e32 v188, 32, v160
	v_mul_f32_e32 v108, v108, v126
	v_mul_f32_e32 v107, v107, v112
	v_mul_f32_e32 v106, v106, v110
	v_or_b32_e32 v135, 48, v160
	v_cvt_pk_bf16_f32 v106, v106, v107
	v_cvt_pk_bf16_f32 v107, v108, v109
	v_mad_i64_i32 v[108:109], s[10:11], v188, s17, v[128:129]
	v_lshl_add_u64 v[108:109], v[108:109], 0, v[124:125]
	v_pk_mul_f32 v[104:105], v[104:105], v[134:135] op_sel_hi:[1,0]
	v_mov_b32_e32 v208, v106
	v_mov_b32_e32 v209, v107
	v_mov_b32_dpp v106, v105 row_ror:1 row_mask:0xf bank_mask:0xf
	v_mov_b32_dpp v126, v105 row_ror:2 row_mask:0xf bank_mask:0xf
	v_mov_b32_e32 v107, v141
	v_mov_b32_dpp v143, v104 row_ror:2 row_mask:0xf bank_mask:0xf
	v_pk_mul_f32 v[102:103], v[102:103], v[134:135] op_sel_hi:[1,0]
	s_waitcnt lgkmcnt(2)
	v_cndmask_b32_e64 v185, v106, v148, s[40:41]
	v_mov_b32_e32 v106, v105
	s_waitcnt lgkmcnt(1)
	v_cndmask_b32_e64 v126, v204, v126, s[42:43]
	v_fma_f32 v126, v117, v126, v121
	v_fma_f32 v107, v107, v185, v126
	v_fma_f32 v126, v106, v184, v107
	v_mul_f32_e32 v106, 0xbfb8aa3b, v126
	v_exp_f32_e32 v106, v106
	v_mov_b32_dpp v107, v104 row_ror:1 row_mask:0xf bank_mask:0xf
	v_mov_b32_dpp v112, v103 row_ror:1 row_mask:0xf bank_mask:0xf
	v_mov_b32_dpp v113, v103 row_ror:2 row_mask:0xf bank_mask:0xf
	v_add_f32_e32 v106, 1.0, v106
	v_rcp_f32_e32 v148, v106
	s_waitcnt lgkmcnt(2)
	v_cndmask_b32_e64 v183, v107, v127, s[40:41]
	v_mov_b32_e32 v106, v104
	v_mov_b32_e32 v107, v140
	v_cndmask_b32_e64 v127, v186, v143, s[42:43]
	v_fma_f32 v127, v116, v127, v120
	v_fma_f32 v107, v107, v183, v127
	v_fma_f32 v127, v106, v182, v107
	v_mul_f32_e32 v106, 0xbfb8aa3b, v127
	v_exp_f32_e32 v106, v106
	v_pk_mul_f32 v[100:101], v[100:101], v[134:135] op_sel_hi:[1,0]
	v_mul_f32_e32 v107, v126, v148
	v_mov_b32_dpp v110, v102 row_ror:1 row_mask:0xf bank_mask:0xf
	v_add_f32_e32 v106, 1.0, v106
	v_mov_b32_dpp v111, v102 row_ror:2 row_mask:0xf bank_mask:0xf
	v_mul_f32_e32 v101, v101, v107
	v_rcp_f32_e32 v126, v106
	s_waitcnt lgkmcnt(3)
	v_cndmask_b32_e64 v181, v112, v201, s[40:41]
	v_mov_b32_e32 v106, v103
	v_mov_b32_e32 v107, v139
	s_waitcnt lgkmcnt(2)
	v_cndmask_b32_e64 v112, v202, v113, s[42:43]
	v_fma_f32 v112, v115, v112, v119
	v_fma_f32 v107, v107, v181, v112
	v_fma_f32 v112, v106, v180, v107
	v_mul_f32_e32 v106, 0xbfb8aa3b, v112
	v_exp_f32_e32 v113, v106
	s_waitcnt lgkmcnt(1)
	v_cndmask_b32_e64 v179, v110, v137, s[40:41]
	v_mov_b32_e32 v106, v102
	v_mov_b32_e32 v107, v138
	s_waitcnt lgkmcnt(0)
	v_cndmask_b32_e64 v110, v163, v111, s[42:43]
	v_fma_f32 v110, v114, v110, v118
	v_fma_f32 v107, v107, v179, v110
	v_fma_f32 v106, v106, v178, v107
	v_mul_f32_e32 v107, 0xbfb8aa3b, v106
	v_exp_f32_e32 v107, v107
	v_add_f32_e32 v111, 1.0, v113
	v_rcp_f32_e32 v111, v111
	v_mul_f32_e32 v110, v127, v126
	v_add_f32_e32 v107, 1.0, v107
	v_rcp_f32_e32 v107, v107
	v_pk_mul_f32 v[98:99], v[98:99], v[134:135] op_sel_hi:[1,0]
	v_mul_f32_e32 v100, v100, v110
	v_mul_f32_e32 v110, v112, v111
	v_mul_f32_e32 v106, v106, v107
	v_mul_f32_e32 v99, v99, v110
	v_mul_f32_e32 v98, v98, v106
	v_cvt_pk_bf16_f32 v98, v98, v99
	v_cvt_pk_bf16_f32 v99, v100, v101
	v_mad_i64_i32 v[100:101], s[10:11], v135, s17, v[128:129]
	v_readlane_b32 s10, v254, 44
	v_lshl_add_u64 v[110:111], v[100:101], 0, v[124:125]
	v_readlane_b32 s11, v254, 45
	v_mov_b32_e32 v210, v98
	v_mov_b32_e32 v211, v99
	s_nop 0
	v_lshl_add_u64 v[98:99], s[10:11], 0, v[146:147]
	v_lshl_add_u64 v[106:107], v[156:157], 2, v[98:99]
	s_and_saveexec_b64 s[10:11], s[44:45]
	v_readlane_b32 s85, v254, 57
	v_readlane_b32 s93, v254, 58
	s_cbranch_execz .LBB0_47
	global_store_dwordx4 v[106:107], v[102:105], off
; __device__ __forceinline__ unsigned cvt_pk_bf16(float lo, float hi) { unsigned r; asm volatile("v_cvt_pk_bf16_f32 %0, %1, %2" : "=v"(r) : "v"(lo), "v"(hi)); return r; }
;     __device__ __forceinline__ void operator()(const f32x4 (&acc)[2][2][4][2], const Unit& u, int wr, int wc, int fr, int fq) const {
;     ...
;             for (int m = 0; m < 4; ++m) rs[ai][m] = __builtin_amdgcn_rsqf((float)ss[u.pm * BM + ai * HALF + wr * 64 + m * 16 + fr] * (1.f / (2048.f * 262144.f)) + 1e-6f);
; #pragma unroll
;         for (int n = 0; n < 2; ++n) {
;             const int cbase = 128 * u.pn + 32 * wc + 16 * n + 4 * fq;
;             const f32x4 w0 = *(const f32x4*)(cw + cbase), w1 = *(const f32x4*)(cw + FF + cbase), w2 = *(const f32x4*)(cw + 2 * FF + cbase), b4 = *(const f32x4*)(cb + cbase);
; #pragma unroll
;             for (int ai = 0; ai < 2; ++ai) {
;                 const int slab = u.pm * 4 + 2 * ai + wr;
;                 f32x4 r1p = (f32x4){0.f, 0.f, 0.f, 0.f}, r2p = (f32x4){0.f, 0.f, 0.f, 0.f};
; #pragma unroll
;                 for (int m = 0; m < 4; ++m) {
;                     const f32x4 g = acc[ai][1][m][n] * rs[ai][m], v = acc[ai][0][m][n] * rs[ai][m];
;                     f32x4 r1, r2, a;
; #pragma unroll
;                     for (int e = 0; e < 4; ++e) { r1[e] = __shfl(g[e], src1); r2[e] = __shfl(g[e], src2); }
; #pragma unroll
;                     for (int e = 0; e < 4; ++e) {
;                         const float p1 = fr >= 1 ? r1[e] : r1p[e], p2 = fr >= 2 ? r2[e] : r2p[e];
;                         const float gg = b4[e] + w0[e] * p2 + w1[e] * p1 + w2[e] * g[e];
;                         a[e] = gg * __builtin_amdgcn_rcpf(1.f + __expf(-gg)) * v[e];
;                     }
;                     r1p = r1; r2p = r2;
;                     const size_t row = (size_t)(u.pm * BM + ai * HALF + wr * 64 + m * 16 + fr);
;                     if (m == 0 && fr < 2) {
;                         *(f32x4*)(GF + (size_t)(slab * 2 + fr) * FF + cbase) = g; *(f32x4*)(VF + (size_t)(slab * 2 + fr) * FF + cbase) = v;
;                     } else {
;                         typedef unsigned u32x2v __attribute__((ext_vector_type(2)));
;                         u32x2v w; w.x = cvt_pk_bf16(a[0], a[1]); w.y = cvt_pk_bf16(a[2], a[3]);
;                         *(u32x2v*)(ACT + row * FF + cbase) = w;
.LBB0_47:
	s_or_b64 exec, exec, s[10:11]
	v_ffbh_u32_e32 v98, v177
	v_min_u32_e32 v100, 32, v98
	v_lshlrev_b64 v[98:99], v100, v[176:177]
	v_min_u32_e32 v98, 1, v98
	v_or_b32_e32 v98, v99, v98
	v_cvt_f32_u32_e32 v98, v98
	v_sub_u32_e32 v99, 32, v100
	v_add_u32_e32 v180, 0x80, v160
	v_mov_b32_e32 v146, v130
	v_ldexp_f32 v98, v98, v99
	v_fmamk_f32 v98, v98, 0x31000000, v232
	v_rsq_f32_e32 v102, v98
	v_mov_b32_e32 v147, v138
	v_mov_b32_e32 v128, v131
	v_mov_b32_e32 v129, v139
	v_pk_mul_f32 v[98:99], v[90:91], v[102:103] op_sel_hi:[1,0]
	v_pk_mul_f32 v[100:101], v[92:93], v[102:103] op_sel_hi:[1,0]
	s_nop 1
	v_mov_b32_dpp v103, v98 row_ror:2 row_mask:0xf bank_mask:0xf
	v_mov_b32_dpp v135, v98 row_ror:1 row_mask:0xf bank_mask:0xf
	v_mov_b32_dpp v177, v99 row_ror:1 row_mask:0xf bank_mask:0xf
	v_mov_b32_dpp v137, v99 row_ror:2 row_mask:0xf bank_mask:0xf
	v_mov_b32_dpp v163, v100 row_ror:1 row_mask:0xf bank_mask:0xf
	v_mov_b32_dpp v143, v100 row_ror:2 row_mask:0xf bank_mask:0xf
	v_mov_b32_dpp v179, v101 row_ror:1 row_mask:0xf bank_mask:0xf
	v_mov_b32_dpp v181, v101 row_ror:2 row_mask:0xf bank_mask:0xf
	s_waitcnt lgkmcnt(7)
	v_pk_mul_f32 v[92:93], v[96:97], v[102:103] op_sel_hi:[1,0]
	v_pk_mul_f32 v[90:91], v[94:95], v[102:103] op_sel_hi:[1,0]
	v_mov_b32_e32 v148, v132
	v_mov_b32_e32 v149, v140
	v_mov_b32_e32 v126, v133
	v_mov_b32_e32 v127, v141
	s_and_saveexec_b64 s[10:11], s[42:43]
	s_xor_b64 s[10:11], exec, s[10:11]
	s_cbranch_execz .LBB0_49
	v_mov_b32_e32 v126, v133
	v_mov_b32_e32 v127, v141
	v_mov_b32_e32 v178, v101
	s_waitcnt lgkmcnt(1)
	s_waitcnt lgkmcnt(0)
	v_fma_f32 v96, v117, v181, v121
	v_fma_f32 v95, v127, v179, v96
	v_fma_f32 v94, v126, v178, v95
	v_mul_f32_e32 v95, 0xbfb8aa3b, v94
	v_exp_f32_e32 v95, v95
	v_mov_b32_e32 v133, v140
	v_mov_b32_e32 v101, v163
	v_mov_b32_e32 v128, v131
	v_add_f32_e32 v95, 1.0, v95
	v_rcp_f32_e32 v95, v95
	v_mov_b32_e32 v129, v139
	v_mov_b32_e32 v176, v99
	v_mov_b32_e32 v131, v138
	v_mul_f32_e32 v94, v94, v95
	v_mul_f32_e32 v96, v93, v94
	v_fma_f32 v93, v116, v143, v120
	v_fma_f32 v93, v133, v101, v93
	v_fma_f32 v93, v132, v100, v93
	v_mul_f32_e32 v94, 0xbfb8aa3b, v93
	v_exp_f32_e32 v94, v94
	v_fma_f32 v95, v115, v137, v119
	v_mov_b32_e32 v99, v135
	v_mov_b64_e32 v[148:149], v[132:133]
	v_add_f32_e32 v94, 1.0, v94
	v_rcp_f32_e32 v94, v94
	v_mov_b64_e32 v[146:147], v[130:131]
	v_mul_f32_e32 v93, v93, v94
	v_mul_f32_e32 v94, v92, v93
	s_nop 0
	v_fma_f32 v93, v129, v177, v95
	v_fma_f32 v92, v128, v176, v93
	v_mul_f32_e32 v93, 0xbfb8aa3b, v92
	v_exp_f32_e32 v93, v93
	v_fma_f32 v95, v114, v103, v118
	v_add_f32_e32 v93, 1.0, v93
	v_rcp_f32_e32 v93, v93
	s_nop 0
	v_mul_f32_e32 v92, v92, v93
	v_mul_f32_e32 v91, v91, v92
	s_nop 0
	v_fma_f32 v93, v131, v99, v95
	v_fma_f32 v92, v130, v98, v93
	v_mul_f32_e32 v93, 0xbfb8aa3b, v92
	v_exp_f32_e32 v93, v93
	s_nop 0
	v_add_f32_e32 v93, 1.0, v93
	v_rcp_f32_e32 v93, v93
	s_nop 0
	v_mul_f32_e32 v92, v92, v93
	v_mul_f32_e32 v90, v90, v92
	v_mov_b64_e32 v[92:93], s[48:49]
	v_mad_i64_i32 v[92:93], s[68:69], v180, s17, v[92:93]
	v_cvt_pk_bf16_f32 v90, v90, v91
	v_cvt_pk_bf16_f32 v91, v94, v96
	v_lshl_add_u64 v[92:93], v[156:157], 1, v[92:93]
	v_mov_b32_e32 v212, v90
	v_mov_b32_e32 v213, v91

; __device__ __forceinline__ unsigned cvt_pk_bf16(float lo, float hi) { unsigned r; asm volatile("v_cvt_pk_bf16_f32 %0, %1, %2" : "=v"(r) : "v"(lo), "v"(hi)); return r; }
;     __device__ __forceinline__ void operator()(const f32x4 (&acc)[2][2][4][2], const Unit& u, int wr, int wc, int fr, int fq) const {
;     ...
;             for (int m = 0; m < 4; ++m) rs[ai][m] = __builtin_amdgcn_rsqf((float)ss[u.pm * BM + ai * HALF + wr * 64 + m * 16 + fr] * (1.f / (2048.f * 262144.f)) + 1e-6f);
; #pragma unroll
;         for (int n = 0; n < 2; ++n) {
;             const int cbase = 128 * u.pn + 32 * wc + 16 * n + 4 * fq;
;             const f32x4 w0 = *(const f32x4*)(cw + cbase), w1 = *(const f32x4*)(cw + FF + cbase), w2 = *(const f32x4*)(cw + 2 * FF + cbase), b4 = *(const f32x4*)(cb + cbase);
; #pragma unroll
;             for (int ai = 0; ai < 2; ++ai) {
;                 const int slab = u.pm * 4 + 2 * ai + wr;
;                 f32x4 r1p = (f32x4){0.f, 0.f, 0.f, 0.f}, r2p = (f32x4){0.f, 0.f, 0.f, 0.f};
; #pragma unroll
;                 for (int m = 0; m < 4; ++m) {
;                     const f32x4 g = acc[ai][1][m][n] * rs[ai][m], v = acc[ai][0][m][n] * rs[ai][m];
;                     f32x4 r1, r2, a;
; #pragma unroll
;                     for (int e = 0; e < 4; ++e) { r1[e] = __shfl(g[e], src1); r2[e] = __shfl(g[e], src2); }
; #pragma unroll
;                     for (int e = 0; e < 4; ++e) {
;                         const float p1 = fr >= 1 ? r1[e] : r1p[e], p2 = fr >= 2 ? r2[e] : r2p[e];
;                         const float gg = b4[e] + w0[e] * p2 + w1[e] * p1 + w2[e] * g[e];
;                         a[e] = gg * __builtin_amdgcn_rcpf(1.f + __expf(-gg)) * v[e];
;                     }
;                     r1p = r1; r2p = r2;
;                     const size_t row = (size_t)(u.pm * BM + ai * HALF + wr * 64 + m * 16 + fr);
;                     if (m == 0 && fr < 2) {
;                         *(f32x4*)(GF + (size_t)(slab * 2 + fr) * FF + cbase) = g; *(f32x4*)(VF + (size_t)(slab * 2 + fr) * FF + cbase) = v;
;                     } else {
;                         typedef unsigned u32x2v __attribute__((ext_vector_type(2)));
;                         u32x2v w; w.x = cvt_pk_bf16(a[0], a[1]); w.y = cvt_pk_bf16(a[2], a[3]);
;                         *(u32x2v*)(ACT + row * FF + cbase) = w;
.LBB0_51:
	s_or_b64 exec, exec, s[10:11]
	s_nop 0
	v_ffbh_u32_e32 v90, v175
	v_min_u32_e32 v93, 32, v90
	v_lshlrev_b64 v[90:91], v93, v[174:175]
	v_min_u32_e32 v90, 1, v90
	v_or_b32_e32 v90, v91, v90
	v_cvt_f32_u32_e32 v90, v90
	v_sub_u32_e32 v91, 32, v93
	v_add_u32_e32 v92, s12, v197
	s_movk_i32 s10, 0x5600
	v_ldexp_f32 v90, v90, v91
	v_mad_i64_i32 v[100:101], s[10:11], v92, s10, 0
	v_fmamk_f32 v92, v90, 0x31000000, v232
	v_rsq_f32_e32 v94, v92
	v_add_u32_e32 v95, 0x90, v160
	v_ffbh_u32_e32 v90, v173
	v_min_u32_e32 v93, 32, v90
	v_pk_mul_f32 v[88:89], v[88:89], v[94:95] op_sel_hi:[1,0]
	s_nop 1
	v_mov_b32_dpp v131, v89 row_ror:1 row_mask:0xf bank_mask:0xf
	v_mov_b32_dpp v138, v89 row_ror:2 row_mask:0xf bank_mask:0xf
	v_mov_b32_e32 v96, v89
	v_lshlrev_b64 v[90:91], v93, v[172:173]
	v_min_u32_e32 v90, 1, v90
	s_waitcnt lgkmcnt(1)
	v_cndmask_b32_e64 v97, v131, v179, s[40:41]
	s_waitcnt lgkmcnt(0)
	v_cndmask_b32_e64 v89, v181, v138, s[42:43]
	v_fma_f32 v89, v117, v89, v121
	v_fma_f32 v89, v127, v97, v89
	v_fma_f32 v96, v126, v96, v89
	v_mul_f32_e32 v89, 0xbfb8aa3b, v96
	v_or_b32_e32 v90, v91, v90
	v_exp_f32_e32 v89, v89
	v_mov_b32_dpp v97, v88 row_ror:1 row_mask:0xf bank_mask:0xf
	v_mov_b32_dpp v140, v88 row_ror:2 row_mask:0xf bank_mask:0xf
	v_cvt_f32_u32_e32 v90, v90
	v_sub_u32_e32 v91, 32, v93
	v_add_f32_e32 v89, 1.0, v89
	v_rcp_f32_e32 v98, v89
	v_ldexp_f32 v90, v90, v91
	s_waitcnt lgkmcnt(1)
	v_cndmask_b32_e64 v89, v97, v163, s[40:41]
	s_waitcnt lgkmcnt(0)
	v_cndmask_b32_e64 v99, v143, v140, s[42:43]
	v_fmamk_f32 v92, v90, 0x31000000, v232
	v_ffbh_u32_e32 v90, v171
	v_fma_f32 v99, v116, v99, v120
	v_min_u32_e32 v93, 32, v90
	v_fma_f32 v89, v149, v89, v99
	v_lshlrev_b64 v[90:91], v93, v[170:171]
	v_fma_f32 v99, v148, v88, v89
	v_min_u32_e32 v90, 1, v90
	v_pk_mul_f32 v[86:87], v[86:87], v[94:95] op_sel_hi:[1,0]
	v_mul_f32_e32 v88, 0xbfb8aa3b, v99
	v_or_b32_e32 v90, v91, v90
	v_mov_b32_dpp v133, v87 row_ror:1 row_mask:0xf bank_mask:0xf
	v_mov_b32_dpp v139, v87 row_ror:2 row_mask:0xf bank_mask:0xf
	v_exp_f32_e32 v88, v88
	v_cvt_f32_u32_e32 v90, v90
	v_sub_u32_e32 v93, 32, v93
	v_pk_mul_f32 v[84:85], v[84:85], v[94:95] op_sel_hi:[1,0]
	v_mul_f32_e32 v89, v96, v98
	v_add_f32_e32 v88, 1.0, v88
	v_ldexp_f32 v90, v90, v93
	v_mov_b32_dpp v93, v86 row_ror:1 row_mask:0xf bank_mask:0xf
	v_mov_b32_dpp v132, v86 row_ror:2 row_mask:0xf bank_mask:0xf
	v_mul_f32_e32 v85, v85, v89
	v_rcp_f32_e32 v96, v88
	s_waitcnt lgkmcnt(3)
	v_cndmask_b32_e64 v89, v133, v177, s[40:41]
	v_mov_b32_e32 v88, v87
	s_waitcnt lgkmcnt(2)
	v_cndmask_b32_e64 v87, v137, v139, s[42:43]
	v_fma_f32 v87, v115, v87, v119
	v_fma_f32 v87, v129, v89, v87
	v_fma_f32 v88, v128, v88, v87
	v_mul_f32_e32 v87, 0xbfb8aa3b, v88
	v_exp_f32_e32 v89, v87
	s_waitcnt lgkmcnt(1)
	v_cndmask_b32_e64 v87, v93, v135, s[40:41]
	s_waitcnt lgkmcnt(0)
	v_cndmask_b32_e64 v98, v103, v132, s[42:43]
	v_fma_f32 v98, v114, v98, v118
	v_fma_f32 v87, v147, v87, v98
	v_fma_f32 v86, v146, v86, v87
	v_mul_f32_e32 v87, 0xbfb8aa3b, v86
	v_exp_f32_e32 v87, v87
	v_add_f32_e32 v89, 1.0, v89
	v_rcp_f32_e32 v89, v89
	v_rsq_f32_e32 v92, v92
	v_add_f32_e32 v87, 1.0, v87
	v_rcp_f32_e32 v87, v87
	v_pk_mul_f32 v[82:83], v[82:83], v[94:95] op_sel_hi:[1,0]
	v_mul_f32_e32 v96, v99, v96
	v_mul_f32_e32 v88, v88, v89
	v_mul_f32_e32 v86, v86, v87
	v_mul_f32_e32 v84, v84, v96
	v_mul_f32_e32 v83, v83, v88
	v_mul_f32_e32 v82, v82, v86
	v_cvt_pk_bf16_f32 v82, v82, v83
	v_cvt_pk_bf16_f32 v83, v84, v85
	v_mov_b64_e32 v[84:85], s[48:49]
	v_mad_i64_i32 v[86:87], s[10:11], v95, s17, v[84:85]
	v_pk_mul_f32 v[80:81], v[80:81], v[92:93] op_sel_hi:[1,0]
	v_lshl_add_u64 v[98:99], v[86:87], 0, v[124:125]
	s_nop 1
	v_mov_b32_dpp v87, v81 row_ror:1 row_mask:0xf bank_mask:0xf
	v_mov_b32_dpp v95, v81 row_ror:2 row_mask:0xf bank_mask:0xf
	v_mov_b32_e32 v214, v82
	v_mov_b32_e32 v215, v83
	v_mov_b32_e32 v82, v81
	v_pk_mul_f32 v[78:79], v[78:79], v[92:93] op_sel_hi:[1,0]
	s_waitcnt lgkmcnt(1)
	v_cndmask_b32_e64 v83, v87, v131, s[40:41]
	s_waitcnt lgkmcnt(0)
	v_cndmask_b32_e64 v81, v138, v95, s[42:43]
	v_fma_f32 v81, v117, v81, v121
	v_fma_f32 v81, v127, v83, v81
	v_fma_f32 v82, v126, v82, v81
	v_mul_f32_e32 v81, 0xbfb8aa3b, v82
	v_exp_f32_e32 v81, v81
	v_mov_b32_dpp v83, v80 row_ror:1 row_mask:0xf bank_mask:0xf
	v_mov_b32_dpp v131, v80 row_ror:2 row_mask:0xf bank_mask:0xf
	v_mov_b32_dpp v89, v79 row_ror:1 row_mask:0xf bank_mask:0xf
	v_add_f32_e32 v81, 1.0, v81
	v_rcp_f32_e32 v96, v81
	s_waitcnt lgkmcnt(2)
	v_cndmask_b32_e64 v81, v83, v97, s[40:41]
	s_waitcnt lgkmcnt(1)
	v_cndmask_b32_e64 v97, v140, v131, s[42:43]
	v_fma_f32 v97, v116, v97, v120
	v_fma_f32 v81, v149, v81, v97
	v_fma_f32 v97, v148, v80, v81
	v_mul_f32_e32 v80, 0xbfb8aa3b, v97
	v_mov_b32_dpp v103, v79 row_ror:2 row_mask:0xf bank_mask:0xf
	v_exp_f32_e32 v80, v80
	v_pk_mul_f32 v[76:77], v[76:77], v[92:93] op_sel_hi:[1,0]
	v_mul_f32_e32 v81, v82, v96
	v_mov_b32_dpp v86, v78 row_ror:1 row_mask:0xf bank_mask:0xf
	v_add_f32_e32 v80, 1.0, v80
	v_mov_b32_dpp v88, v78 row_ror:2 row_mask:0xf bank_mask:0xf
	v_mul_f32_e32 v77, v77, v81
	v_rcp_f32_e32 v82, v80
	s_waitcnt lgkmcnt(3)
	v_cndmask_b32_e64 v81, v89, v133, s[40:41]
	v_mov_b32_e32 v80, v79
	s_waitcnt lgkmcnt(2)
	v_cndmask_b32_e64 v79, v139, v103, s[42:43]
	v_fma_f32 v79, v115, v79, v119
	v_fma_f32 v79, v129, v81, v79
	v_fma_f32 v80, v128, v80, v79
	v_mul_f32_e32 v79, 0xbfb8aa3b, v80
	v_pk_mul_f32 v[74:75], v[74:75], v[92:93] op_sel_hi:[1,0]
	v_exp_f32_e32 v81, v79
	s_waitcnt lgkmcnt(1)
	v_cndmask_b32_e64 v79, v86, v93, s[40:41]
	s_waitcnt lgkmcnt(0)
;     __device__ __forceinline__ void operator()(const f32x4 (&acc)[2][2][4][2], const Unit& u, int wr, int wc, int fr, int fq) const {
;     ...
;             for (int m = 0; m < 4; ++m) rs[ai][m] = __builtin_amdgcn_rsqf((float)ss[u.pm * BM + ai * HALF + wr * 64 + m * 16 + fr] * (1.f / (2048.f * 262144.f)) + 1e-6f);
; #pragma unroll
;         for (int n = 0; n < 2; ++n) {
;             const int cbase = 128 * u.pn + 32 * wc + 16 * n + 4 * fq;
;             const f32x4 w0 = *(const f32x4*)(cw + cbase), w1 = *(const f32x4*)(cw + FF + cbase), w2 = *(const f32x4*)(cw + 2 * FF + cbase), b4 = *(const f32x4*)(cb + cbase);
; #pragma unroll
;             for (int ai = 0; ai < 2; ++ai) {
;                 const int slab = u.pm * 4 + 2 * ai + wr;
;                 f32x4 r1p = (f32x4){0.f, 0.f, 0.f, 0.f}, r2p = (f32x4){0.f, 0.f, 0.f, 0.f};
; #pragma unroll
;                 for (int m = 0; m < 4; ++m) {
;                     const f32x4 g = acc[ai][1][m][n] * rs[ai][m], v = acc[ai][0][m][n] * rs[ai][m];
;                     f32x4 r1, r2, a;
; #pragma unroll
;                     for (int e = 0; e < 4; ++e) { r1[e] = __shfl(g[e], src1); r2[e] = __shfl(g[e], src2); }
; #pragma unroll
;                     for (int e = 0; e < 4; ++e) {
;                         const float p1 = fr >= 1 ? r1[e] : r1p[e], p2 = fr >= 2 ? r2[e] : r2p[e];
;                         const float gg = b4[e] + w0[e] * p2 + w1[e] * p1 + w2[e] * g[e];
;                         a[e] = gg * __builtin_amdgcn_rcpf(1.f + __expf(-gg)) * v[e];
;                     }
;                     r1p = r1; r2p = r2;
;                     const size_t row = (size_t)(u.pm * BM + ai * HALF + wr * 64 + m * 16 + fr);
;                     if (m == 0 && fr < 2) {
;                         *(f32x4*)(GF + (size_t)(slab * 2 + fr) * FF + cbase) = g; *(f32x4*)(VF + (size_t)(slab * 2 + fr) * FF + cbase) = v;
;                     } else {
;                         typedef unsigned u32x2v __attribute__((ext_vector_type(2)));
;                         u32x2v w; w.x = cvt_pk_bf16(a[0], a[1]); w.y = cvt_pk_bf16(a[2], a[3]);
;                         *(u32x2v*)(ACT + row * FF + cbase) = w;
;                     }
;                     if (m == 3 && fr >= 14) *(f32x4*)(GL + (size_t)(slab * 2 + fr - 14) * FF + cbase) = g;
	v_cndmask_b32_e64 v93, v132, v88, s[42:43]
	v_fma_f32 v93, v114, v93, v118
	v_fma_f32 v79, v147, v79, v93
	v_fma_f32 v78, v146, v78, v79
	v_mul_f32_e32 v79, 0xbfb8aa3b, v78
	v_exp_f32_e32 v79, v79
	v_add_f32_e32 v81, 1.0, v81
	v_rcp_f32_e32 v81, v81
	v_fmamk_f32 v90, v90, 0x31000000, v232
	v_add_f32_e32 v79, 1.0, v79
	v_rcp_f32_e32 v79, v79
	v_rsq_f32_e32 v90, v90
	v_mul_f32_e32 v82, v97, v82
	v_mul_f32_e32 v80, v80, v81
	v_mul_f32_e32 v78, v78, v79
	v_add_u32_e32 v130, 0xa0, v160
	v_mul_f32_e32 v76, v76, v82
	v_mul_f32_e32 v75, v75, v80
	v_mul_f32_e32 v74, v74, v78
	v_add_u32_e32 v91, 0xb0, v160
	v_cvt_pk_bf16_f32 v74, v74, v75
	v_cvt_pk_bf16_f32 v75, v76, v77
	v_mad_i64_i32 v[76:77], s[10:11], v130, s17, v[84:85]
	v_lshl_add_u64 v[96:97], v[76:77], 0, v[124:125]
	v_pk_mul_f32 v[72:73], v[72:73], v[90:91] op_sel_hi:[1,0]
	v_mov_b32_e32 v216, v74
	v_mov_b32_e32 v217, v75
	v_mov_b32_dpp v74, v73 row_ror:1 row_mask:0xf bank_mask:0xf
	v_mov_b32_dpp v79, v73 row_ror:2 row_mask:0xf bank_mask:0xf
	v_mov_b32_dpp v81, v72 row_ror:2 row_mask:0xf bank_mask:0xf
	v_pk_mul_f32 v[70:71], v[70:71], v[90:91] op_sel_hi:[1,0]
	s_nop 1
	v_mov_b32_dpp v78, v71 row_ror:1 row_mask:0xf bank_mask:0xf
	s_waitcnt lgkmcnt(3)
	v_cndmask_b32_e64 v75, v74, v87, s[40:41]
	v_mov_b32_e32 v74, v73
	s_waitcnt lgkmcnt(2)
	v_cndmask_b32_e64 v79, v95, v79, s[42:43]
	v_fma_f32 v79, v117, v79, v121
	v_fma_f32 v75, v127, v75, v79
	v_fma_f32 v79, v126, v74, v75
	v_mul_f32_e32 v74, 0xbfb8aa3b, v79
	v_exp_f32_e32 v74, v74
	v_mov_b32_dpp v75, v72 row_ror:1 row_mask:0xf bank_mask:0xf
	s_waitcnt lgkmcnt(2)
	v_cndmask_b32_e64 v81, v131, v81, s[42:43]
	v_fma_f32 v81, v116, v81, v120
	v_add_f32_e32 v74, 1.0, v74
	v_rcp_f32_e32 v82, v74
	s_waitcnt lgkmcnt(0)
	v_cndmask_b32_e64 v75, v75, v83, s[40:41]
	v_mov_b32_e32 v74, v72
	v_mov_b32_dpp v80, v71 row_ror:2 row_mask:0xf bank_mask:0xf
	v_fma_f32 v75, v149, v75, v81
	v_fma_f32 v81, v148, v74, v75
	v_mul_f32_e32 v74, 0xbfb8aa3b, v81
	v_exp_f32_e32 v74, v74
	v_pk_mul_f32 v[68:69], v[68:69], v[90:91] op_sel_hi:[1,0]
	v_mul_f32_e32 v75, v79, v82
	v_mov_b32_dpp v76, v70 row_ror:1 row_mask:0xf bank_mask:0xf
	v_add_f32_e32 v74, 1.0, v74
	v_mov_b32_dpp v77, v70 row_ror:2 row_mask:0xf bank_mask:0xf
	v_mul_f32_e32 v69, v69, v75
	v_rcp_f32_e32 v79, v74
	v_cndmask_b32_e64 v75, v78, v89, s[40:41]
	v_mov_b32_e32 v74, v71
	s_waitcnt lgkmcnt(2)
	v_cndmask_b32_e64 v78, v103, v80, s[42:43]
	v_fma_f32 v78, v115, v78, v119
	v_fma_f32 v75, v129, v75, v78
	v_fma_f32 v78, v128, v74, v75
	v_mul_f32_e32 v74, 0xbfb8aa3b, v78
	v_exp_f32_e32 v80, v74
	s_waitcnt lgkmcnt(1)
	v_cndmask_b32_e64 v75, v76, v86, s[40:41]
	v_mov_b32_e32 v74, v70
	s_waitcnt lgkmcnt(0)
	v_cndmask_b32_e64 v76, v88, v77, s[42:43]
	v_fmac_f32_e32 v118, v114, v76
	v_fma_f32 v75, v147, v75, v118
	v_fma_f32 v74, v146, v74, v75
	v_mul_f32_e32 v75, 0xbfb8aa3b, v74
	v_exp_f32_e32 v75, v75
	v_add_f32_e32 v77, 1.0, v80
	v_rcp_f32_e32 v77, v77
	v_mul_f32_e32 v76, v81, v79
	v_add_f32_e32 v75, 1.0, v75
	v_rcp_f32_e32 v75, v75
	v_pk_mul_f32 v[66:67], v[66:67], v[90:91] op_sel_hi:[1,0]
	v_mul_f32_e32 v68, v68, v76
	v_mul_f32_e32 v76, v78, v77
	v_mul_f32_e32 v74, v74, v75
	v_mul_f32_e32 v67, v67, v76
	v_mul_f32_e32 v66, v66, v74
	v_cvt_pk_bf16_f32 v66, v66, v67
	v_cvt_pk_bf16_f32 v67, v68, v69
	v_mad_i64_i32 v[68:69], s[10:11], v91, s17, v[84:85]
	v_readlane_b32 s10, v254, 44
	v_lshl_add_u64 v[88:89], v[68:69], 0, v[124:125]
	v_readlane_b32 s11, v254, 45
	v_mov_b32_e32 v218, v66
	v_mov_b32_e32 v219, v67
	s_nop 0
	v_lshl_add_u64 v[66:67], s[10:11], 0, v[100:101]
	v_lshl_add_u64 v[86:87], v[156:157], 2, v[66:67]
	s_and_saveexec_b64 s[10:11], s[44:45]
	s_cbranch_execz .LBB0_53
	global_store_dwordx4 v[86:87], v[70:73], off
.LBB0_53:
	s_or_b64 exec, exec, s[10:11]
	s_nop 0
	v_or_b32_e32 v70, 16, v156
	v_ashrrev_i32_e32 v71, 31, v70
	v_lshlrev_b64 v[70:71], 2, v[70:71]
	v_lshl_add_u64 v[72:73], s[60:61], 0, v[70:71]
	v_lshl_add_u64 v[70:71], s[62:63], 0, v[70:71]
	ds_read_b128 v[66:69], v166 offset:64
	ds_read_b128 v[78:81], v166 offset:576
	ds_read_b128 v[74:77], v166 offset:1088
	s_nop 0
	ds_read_b128 v[70:73], v166 offset:1600
	v_mov_b32_e32 v163, v162
	v_mov_b32_e32 v120, v162
	v_mov_b32_e32 v121, v162
	v_pk_mul_f32 v[84:85], v[60:61], v[120:121]
	v_pk_mul_f32 v[82:83], v[58:59], v[162:163]
	s_nop 1
	v_mov_b32_dpp v101, v82 row_ror:1 row_mask:0xf bank_mask:0xf
	v_mov_b32_dpp v91, v82 row_ror:2 row_mask:0xf bank_mask:0xf
	v_mov_b32_dpp v115, v83 row_ror:1 row_mask:0xf bank_mask:0xf
	v_mov_b32_dpp v93, v83 row_ror:2 row_mask:0xf bank_mask:0xf
	v_mov_b32_dpp v117, v84 row_ror:1 row_mask:0xf bank_mask:0xf
	v_mov_b32_dpp v95, v84 row_ror:2 row_mask:0xf bank_mask:0xf
	v_mov_b32_dpp v119, v85 row_ror:1 row_mask:0xf bank_mask:0xf
	v_mov_b32_dpp v103, v85 row_ror:2 row_mask:0xf bank_mask:0xf
	v_pk_mul_f32 v[60:61], v[64:65], v[120:121]
	v_pk_mul_f32 v[58:59], v[62:63], v[162:163]
	s_and_saveexec_b64 s[10:11], s[42:43]
	s_xor_b64 s[10:11], exec, s[10:11]
	s_cbranch_execz .LBB0_55
	v_mov_b32_e32 v62, v85
	s_waitcnt lgkmcnt(0)
	v_mov_b32_e32 v63, v81
	s_waitcnt lgkmcnt(0)
	v_mov_b32_e32 v118, v77
	s_waitcnt lgkmcnt(1)
	s_waitcnt lgkmcnt(0)
	v_fma_f32 v64, v69, v103, v73
	v_fma_f32 v63, v63, v119, v64
	v_fma_f32 v62, v62, v118, v63
	v_mul_f32_e32 v63, 0xbfb8aa3b, v62
	v_exp_f32_e32 v63, v63
	v_mov_b32_e32 v85, v80
	v_mov_b32_e32 v116, v76
	v_mov_b32_e32 v114, v75
	v_add_f32_e32 v63, 1.0, v63
	v_rcp_f32_e32 v63, v63
	v_mov_b32_e32 v100, v74
	v_mul_f32_e32 v62, v62, v63
	v_mul_f32_e32 v64, v61, v62
	v_fma_f32 v61, v68, v95, v72
	v_fma_f32 v61, v85, v117, v61
	v_fma_f32 v61, v84, v116, v61
	v_mul_f32_e32 v62, 0xbfb8aa3b, v61
	v_exp_f32_e32 v62, v62
	v_fma_f32 v63, v67, v93, v71
	v_add_f32_e32 v62, 1.0, v62
	v_rcp_f32_e32 v62, v62
	s_nop 0
	v_mul_f32_e32 v61, v61, v62
	v_mul_f32_e32 v62, v60, v61
	v_mov_b32_e32 v60, v83
	v_mov_b32_e32 v61, v79
	v_mov_b32_e32 v83, v78
	v_fma_f32 v61, v61, v115, v63
	v_fma_f32 v60, v60, v114, v61
	v_mul_f32_e32 v61, 0xbfb8aa3b, v60
	v_exp_f32_e32 v61, v61
	v_fma_f32 v63, v66, v91, v70
	v_add_f32_e32 v61, 1.0, v61
	v_rcp_f32_e32 v61, v61
	s_nop 0
	v_mul_f32_e32 v60, v60, v61
	v_mul_f32_e32 v59, v59, v60
	s_nop 0
	v_fma_f32 v61, v83, v101, v63
	v_fma_f32 v60, v82, v100, v61
	v_mul_f32_e32 v61, 0xbfb8aa3b, v60
	v_exp_f32_e32 v61, v61
	s_nop 0
	v_add_f32_e32 v61, 1.0, v61
	v_rcp_f32_e32 v61, v61
	s_nop 0
	v_mul_f32_e32 v60, v60, v61
	v_mul_f32_e32 v58, v58, v60
	v_mov_b64_e32 v[60:61], s[48:49]
	v_mad_i64_i32 v[60:61], s[12:13], v160, s17, v[60:61]
	v_cvt_pk_bf16_f32 v58, v58, v59
	v_cvt_pk_bf16_f32 v59, v62, v64
	v_lshl_add_u64 v[60:61], v[156:157], 1, v[60:61]
	v_mov_b32_e32 v64, v77
	v_mov_b32_e32 v62, v75
	s_nop 1
	v_permlane16_swap_b32_e32 v220, v58
	v_permlane16_swap_b32_e32 v221, v59
	v_mov_b32_e32 v222, v58
	v_mov_b32_e32 v223, v59
	v_add_co_u32_e64 v60, s[98:99], v60, v205
	s_nop 1
	v_addc_co_u32_e64 v61, s[98:99], 0, v61, s[98:99]
	global_store_dwordx4 v[60:61], v[220:223], off nt

;     __device__ __forceinline__ void operator()(const f32x4 (&acc)[2][2][4][2], const Unit& u, int wr, int wc, int fr, int fq) const {
;     ...
;             for (int m = 0; m < 4; ++m) rs[ai][m] = __builtin_amdgcn_rsqf((float)ss[u.pm * BM + ai * HALF + wr * 64 + m * 16 + fr] * (1.f / (2048.f * 262144.f)) + 1e-6f);
; #pragma unroll
;         for (int n = 0; n < 2; ++n) {
;             const int cbase = 128 * u.pn + 32 * wc + 16 * n + 4 * fq;
;             const f32x4 w0 = *(const f32x4*)(cw + cbase), w1 = *(const f32x4*)(cw + FF + cbase), w2 = *(const f32x4*)(cw + 2 * FF + cbase), b4 = *(const f32x4*)(cb + cbase);
; #pragma unroll
;             for (int ai = 0; ai < 2; ++ai) {
;                 const int slab = u.pm * 4 + 2 * ai + wr;
;                 f32x4 r1p = (f32x4){0.f, 0.f, 0.f, 0.f}, r2p = (f32x4){0.f, 0.f, 0.f, 0.f};
; #pragma unroll
;                 for (int m = 0; m < 4; ++m) {
;                     const f32x4 g = acc[ai][1][m][n] * rs[ai][m], v = acc[ai][0][m][n] * rs[ai][m];
;                     f32x4 r1, r2, a;
; #pragma unroll
;                     for (int e = 0; e < 4; ++e) { r1[e] = __shfl(g[e], src1); r2[e] = __shfl(g[e], src2); }
; #pragma unroll
;                     for (int e = 0; e < 4; ++e) {
;                         const float p1 = fr >= 1 ? r1[e] : r1p[e], p2 = fr >= 2 ? r2[e] : r2p[e];
;                         const float gg = b4[e] + w0[e] * p2 + w1[e] * p1 + w2[e] * g[e];
;                         a[e] = gg * __builtin_amdgcn_rcpf(1.f + __expf(-gg)) * v[e];
;                     }
;                     r1p = r1; r2p = r2;
;                     const size_t row = (size_t)(u.pm * BM + ai * HALF + wr * 64 + m * 16 + fr);
;                     if (m == 0 && fr < 2) {
;                         *(f32x4*)(GF + (size_t)(slab * 2 + fr) * FF + cbase) = g; *(f32x4*)(VF + (size_t)(slab * 2 + fr) * FF + cbase) = v;
;                     } else {
;                         typedef unsigned u32x2v __attribute__((ext_vector_type(2)));
;                         u32x2v w; w.x = cvt_pk_bf16(a[0], a[1]); w.y = cvt_pk_bf16(a[2], a[3]);
;                         *(u32x2v*)(ACT + row * FF + cbase) = w;
;                     }
;                     if (m == 3 && fr >= 14) *(f32x4*)(GL + (size_t)(slab * 2 + fr - 14) * FF + cbase) = g;
.LBB0_57:
	s_or_b64 exec, exec, s[10:11]
	v_mov_b32_e32 v58, v142
	v_mov_b32_e32 v59, v142
	v_pk_mul_f32 v[56:57], v[56:57], v[58:59]
	s_nop 1
	v_mov_b32_dpp v83, v57 row_ror:1 row_mask:0xf bank_mask:0xf
	v_mov_b32_dpp v114, v57 row_ror:2 row_mask:0xf bank_mask:0xf
	v_mov_b32_e32 v60, v57
	s_waitcnt lgkmcnt(0)
	v_mov_b32_e32 v61, v81
	v_pk_mul_f32 v[52:53], v[52:53], v[58:59]
	s_waitcnt lgkmcnt(1)
	v_cndmask_b32_e64 v65, v83, v119, s[40:41]
	s_waitcnt lgkmcnt(0)
	v_cndmask_b32_e64 v57, v103, v114, s[42:43]
	s_waitcnt lgkmcnt(0)
	v_fma_f32 v57, v69, v57, v73
	v_fma_f32 v57, v61, v65, v57
	v_fma_f32 v60, v60, v64, v57
	v_mul_f32_e32 v57, 0xbfb8aa3b, v60
	v_exp_f32_e32 v57, v57
	v_mov_b32_dpp v61, v56 row_ror:1 row_mask:0xf bank_mask:0xf
	v_mov_b32_dpp v103, v56 row_ror:2 row_mask:0xf bank_mask:0xf
	v_mov_b32_e32 v143, v142
	v_add_f32_e32 v57, 1.0, v57
	v_rcp_f32_e32 v58, v57
	s_waitcnt lgkmcnt(1)
	v_cndmask_b32_e64 v77, v61, v117, s[40:41]
	v_mov_b32_e32 v57, v80
	s_waitcnt lgkmcnt(0)
	v_cndmask_b32_e64 v59, v95, v103, s[42:43]
	v_fma_f32 v59, v68, v59, v72
	v_fma_f32 v57, v57, v77, v59
	v_fma_f32 v59, v56, v76, v57
	v_pk_mul_f32 v[54:55], v[54:55], v[142:143]
	v_mul_f32_e32 v56, 0xbfb8aa3b, v59
	s_nop 1
	v_mov_b32_dpp v85, v55 row_ror:1 row_mask:0xf bank_mask:0xf
	v_mov_b32_dpp v100, v55 row_ror:2 row_mask:0xf bank_mask:0xf
	v_exp_f32_e32 v56, v56
	v_mul_f32_e32 v57, v60, v58
	v_mov_b32_dpp v82, v54 row_ror:1 row_mask:0xf bank_mask:0xf
	v_mov_b32_dpp v84, v54 row_ror:2 row_mask:0xf bank_mask:0xf
	v_add_f32_e32 v56, 1.0, v56
	v_mul_f32_e32 v53, v53, v57
	v_rcp_f32_e32 v58, v56
	s_waitcnt lgkmcnt(3)
	v_cndmask_b32_e64 v63, v85, v115, s[40:41]
	v_mov_b32_e32 v56, v55
	v_mov_b32_e32 v57, v79
	s_waitcnt lgkmcnt(2)
	v_cndmask_b32_e64 v55, v93, v100, s[42:43]
	v_fma_f32 v55, v67, v55, v71
	v_fma_f32 v55, v57, v63, v55
	v_fma_f32 v56, v56, v62, v55
	v_mul_f32_e32 v55, 0xbfb8aa3b, v56
	v_exp_f32_e32 v57, v55
	s_waitcnt lgkmcnt(1)
	v_cndmask_b32_e64 v75, v82, v101, s[40:41]
	v_mov_b32_e32 v55, v78
	s_waitcnt lgkmcnt(0)
	v_cndmask_b32_e64 v60, v91, v84, s[42:43]
	v_fma_f32 v60, v66, v60, v70
	v_fma_f32 v55, v55, v75, v60
	v_fma_f32 v54, v54, v74, v55
	v_mul_f32_e32 v55, 0xbfb8aa3b, v54
	v_exp_f32_e32 v55, v55
	v_add_f32_e32 v57, 1.0, v57
	v_rcp_f32_e32 v57, v57
	v_pk_mul_f32 v[50:51], v[50:51], v[142:143]
	v_add_f32_e32 v55, 1.0, v55
	v_rcp_f32_e32 v55, v55
	v_mul_f32_e32 v56, v56, v57
	v_mul_f32_e32 v58, v59, v58
	v_mul_f32_e32 v51, v51, v56
	v_mul_f32_e32 v54, v54, v55
	v_mul_f32_e32 v50, v50, v54
	v_mul_f32_e32 v52, v52, v58
	v_cvt_pk_bf16_f32 v50, v50, v51
	v_cvt_pk_bf16_f32 v51, v52, v53
	s_nop 1
	v_permlane16_swap_b32_e32 v206, v50
	v_permlane16_swap_b32_e32 v207, v51
	v_mov_b32_e32 v220, v206
	v_mov_b32_e32 v221, v207
	v_mov_b32_e32 v222, v50
	v_mov_b32_e32 v223, v51
	v_add_co_u32_e64 v122, s[98:99], v122, v205
	s_nop 1
	v_addc_co_u32_e64 v123, s[98:99], 0, v123, s[98:99]
	global_store_dwordx4 v[122:123], v[220:223], off nt
	v_mov_b32_e32 v50, v136
	v_mov_b32_e32 v51, v136
	v_pk_mul_f32 v[48:49], v[48:49], v[50:51]
	s_nop 1
	v_mov_b32_dpp v55, v49 row_ror:1 row_mask:0xf bank_mask:0xf
	v_mov_b32_dpp v59, v49 row_ror:2 row_mask:0xf bank_mask:0xf
	v_mov_b32_e32 v52, v49
	v_mov_b32_e32 v53, v81
	v_mov_b32_dpp v60, v48 row_ror:2 row_mask:0xf bank_mask:0xf
	s_waitcnt lgkmcnt(2)
	v_cndmask_b32_e64 v65, v55, v83, s[40:41]
	s_waitcnt lgkmcnt(1)
	v_cndmask_b32_e64 v49, v114, v59, s[42:43]
	v_fma_f32 v49, v69, v49, v73
	v_fma_f32 v49, v53, v65, v49
	v_fma_f32 v52, v52, v64, v49
	v_mul_f32_e32 v49, 0xbfb8aa3b, v52
	v_exp_f32_e32 v49, v49
	v_mov_b32_dpp v53, v48 row_ror:1 row_mask:0xf bank_mask:0xf
	v_pk_mul_f32 v[44:45], v[44:45], v[50:51]
	s_waitcnt lgkmcnt(1)
	v_cndmask_b32_e64 v51, v103, v60, s[42:43]
	v_add_f32_e32 v49, 1.0, v49
	v_rcp_f32_e32 v50, v49
	s_waitcnt lgkmcnt(0)
	v_cndmask_b32_e64 v77, v53, v61, s[40:41]
	v_mov_b32_e32 v49, v80
	v_fma_f32 v51, v68, v51, v72
	v_fma_f32 v49, v49, v77, v51
	v_mov_b32_e32 v137, v136
	v_fma_f32 v51, v48, v76, v49
	v_pk_mul_f32 v[46:47], v[46:47], v[136:137]
	v_mul_f32_e32 v48, 0xbfb8aa3b, v51
	s_nop 1
	v_mov_b32_dpp v57, v47 row_ror:1 row_mask:0xf bank_mask:0xf
	v_mov_b32_dpp v58, v47 row_ror:2 row_mask:0xf bank_mask:0xf
	v_exp_f32_e32 v48, v48
	v_mul_f32_e32 v49, v52, v50
	v_mov_b32_dpp v54, v46 row_ror:1 row_mask:0xf bank_mask:0xf
	v_mov_b32_dpp v56, v46 row_ror:2 row_mask:0xf bank_mask:0xf
	v_add_f32_e32 v48, 1.0, v48
	v_mul_f32_e32 v45, v45, v49
	v_rcp_f32_e32 v50, v48
	s_waitcnt lgkmcnt(3)
	v_cndmask_b32_e64 v63, v57, v85, s[40:41]
	v_mov_b32_e32 v48, v47
	v_mov_b32_e32 v49, v79
	s_waitcnt lgkmcnt(2)
	v_cndmask_b32_e64 v47, v100, v58, s[42:43]
	v_fma_f32 v47, v67, v47, v71
	v_fma_f32 v47, v49, v63, v47
	v_fma_f32 v48, v48, v62, v47
	v_mul_f32_e32 v47, 0xbfb8aa3b, v48
	v_exp_f32_e32 v49, v47
	s_waitcnt lgkmcnt(1)
	v_cndmask_b32_e64 v75, v54, v82, s[40:41]
	v_mov_b32_e32 v47, v78
	s_waitcnt lgkmcnt(0)
	v_cndmask_b32_e64 v52, v84, v56, s[42:43]
	v_fma_f32 v52, v66, v52, v70
	v_fma_f32 v47, v47, v75, v52
	v_fma_f32 v46, v46, v74, v47
	v_mul_f32_e32 v47, 0xbfb8aa3b, v46
	v_exp_f32_e32 v47, v47
	v_add_f32_e32 v49, 1.0, v49
	v_rcp_f32_e32 v49, v49
	v_pk_mul_f32 v[42:43], v[42:43], v[136:137]
	v_add_f32_e32 v47, 1.0, v47
	v_rcp_f32_e32 v47, v47
	v_mul_f32_e32 v48, v48, v49
	v_mul_f32_e32 v50, v51, v50
	v_mul_f32_e32 v43, v43, v48
	v_mul_f32_e32 v46, v46, v47
	v_mul_f32_e32 v42, v42, v46
	v_mul_f32_e32 v44, v44, v50
	v_cvt_pk_bf16_f32 v42, v42, v43
	v_cvt_pk_bf16_f32 v43, v44, v45
	s_nop 1
	v_permlane16_swap_b32_e32 v208, v42
	v_permlane16_swap_b32_e32 v209, v43
	v_mov_b32_e32 v220, v208
	v_mov_b32_e32 v221, v209
	v_mov_b32_e32 v222, v42
	v_mov_b32_e32 v223, v43
	v_add_co_u32_e64 v108, s[98:99], v108, v205
	s_nop 1
	v_addc_co_u32_e64 v109, s[98:99], 0, v109, s[98:99]
	global_store_dwordx4 v[108:109], v[220:223], off nt
	v_mov_b32_e32 v42, v134
	v_mov_b32_e32 v43, v134
	v_pk_mul_f32 v[40:41], v[40:41], v[42:43]
	s_nop 1
	v_mov_b32_dpp v44, v41 row_ror:1 row_mask:0xf bank_mask:0xf
	v_mov_b32_dpp v50, v41 row_ror:2 row_mask:0xf bank_mask:0xf
	v_mov_b32_e32 v45, v81
	v_mov_b32_dpp v51, v40 row_ror:2 row_mask:0xf bank_mask:0xf
	v_pk_mul_f32 v[36:37], v[36:37], v[42:43]
	s_waitcnt lgkmcnt(2)
;     __device__ __forceinline__ void operator()(const f32x4 (&acc)[2][2][4][2], const Unit& u, int wr, int wc, int fr, int fq) const {
;     ...
;             for (int m = 0; m < 4; ++m) rs[ai][m] = __builtin_amdgcn_rsqf((float)ss[u.pm * BM + ai * HALF + wr * 64 + m * 16 + fr] * (1.f / (2048.f * 262144.f)) + 1e-6f);
; #pragma unroll
;         for (int n = 0; n < 2; ++n) {
;             const int cbase = 128 * u.pn + 32 * wc + 16 * n + 4 * fq;
;             const f32x4 w0 = *(const f32x4*)(cw + cbase), w1 = *(const f32x4*)(cw + FF + cbase), w2 = *(const f32x4*)(cw + 2 * FF + cbase), b4 = *(const f32x4*)(cb + cbase);
; #pragma unroll
;             for (int ai = 0; ai < 2; ++ai) {
;                 const int slab = u.pm * 4 + 2 * ai + wr;
;                 f32x4 r1p = (f32x4){0.f, 0.f, 0.f, 0.f}, r2p = (f32x4){0.f, 0.f, 0.f, 0.f};
; #pragma unroll
;                 for (int m = 0; m < 4; ++m) {
;                     const f32x4 g = acc[ai][1][m][n] * rs[ai][m], v = acc[ai][0][m][n] * rs[ai][m];
;                     f32x4 r1, r2, a;
; #pragma unroll
;                     for (int e = 0; e < 4; ++e) { r1[e] = __shfl(g[e], src1); r2[e] = __shfl(g[e], src2); }
; #pragma unroll
;                     for (int e = 0; e < 4; ++e) {
;                         const float p1 = fr >= 1 ? r1[e] : r1p[e], p2 = fr >= 2 ? r2[e] : r2p[e];
;                         const float gg = b4[e] + w0[e] * p2 + w1[e] * p1 + w2[e] * g[e];
;                         a[e] = gg * __builtin_amdgcn_rcpf(1.f + __expf(-gg)) * v[e];
;                     }
;                     r1p = r1; r2p = r2;
;                     const size_t row = (size_t)(u.pm * BM + ai * HALF + wr * 64 + m * 16 + fr);
;                     if (m == 0 && fr < 2) {
;                         *(f32x4*)(GF + (size_t)(slab * 2 + fr) * FF + cbase) = g; *(f32x4*)(VF + (size_t)(slab * 2 + fr) * FF + cbase) = v;
;                     } else {
;                         typedef unsigned u32x2v __attribute__((ext_vector_type(2)));
;                         u32x2v w; w.x = cvt_pk_bf16(a[0], a[1]); w.y = cvt_pk_bf16(a[2], a[3]);
;                         *(u32x2v*)(ACT + row * FF + cbase) = w;
;                     }
;                     if (m == 3 && fr >= 14) *(f32x4*)(GL + (size_t)(slab * 2 + fr - 14) * FF + cbase) = g;
	v_cndmask_b32_e64 v65, v44, v55, s[40:41]
	v_mov_b32_e32 v44, v41
	s_waitcnt lgkmcnt(1)
	v_cndmask_b32_e64 v50, v59, v50, s[42:43]
	v_fma_f32 v50, v69, v50, v73
	v_fma_f32 v45, v45, v65, v50
	v_fma_f32 v44, v44, v64, v45
	v_mul_f32_e32 v45, 0xbfb8aa3b, v44
	v_exp_f32_e32 v45, v45
	v_mov_b32_dpp v50, v40 row_ror:1 row_mask:0xf bank_mask:0xf
	v_mov_b32_e32 v43, v80
	v_mov_b32_e32 v135, v134
	v_add_f32_e32 v42, 1.0, v45
	v_rcp_f32_e32 v45, v42
	s_waitcnt lgkmcnt(0)
	v_cndmask_b32_e64 v77, v50, v53, s[40:41]
	v_mov_b32_e32 v42, v40
	v_cndmask_b32_e64 v50, v60, v51, s[42:43]
	v_fma_f32 v50, v68, v50, v72
	v_fma_f32 v43, v43, v77, v50
	v_fma_f32 v50, v42, v76, v43
	v_pk_mul_f32 v[38:39], v[38:39], v[134:135]
	v_mul_f32_e32 v42, 0xbfb8aa3b, v50
	s_nop 1
	v_mov_b32_dpp v48, v39 row_ror:1 row_mask:0xf bank_mask:0xf
	v_mov_b32_dpp v49, v39 row_ror:2 row_mask:0xf bank_mask:0xf
	v_exp_f32_e32 v42, v42
	v_mul_f32_e32 v43, v44, v45
	v_mov_b32_dpp v46, v38 row_ror:1 row_mask:0xf bank_mask:0xf
	v_mov_b32_dpp v47, v38 row_ror:2 row_mask:0xf bank_mask:0xf
	v_add_f32_e32 v42, 1.0, v42
	v_mul_f32_e32 v37, v37, v43
	v_rcp_f32_e32 v44, v42
	s_waitcnt lgkmcnt(3)
	v_cndmask_b32_e64 v63, v48, v57, s[40:41]
	v_mov_b32_e32 v42, v39
	v_mov_b32_e32 v43, v79
	s_waitcnt lgkmcnt(2)
	v_cndmask_b32_e64 v45, v58, v49, s[42:43]
	v_fma_f32 v45, v67, v45, v71
	v_fma_f32 v43, v43, v63, v45
	v_fma_f32 v45, v42, v62, v43
	v_mul_f32_e32 v42, 0xbfb8aa3b, v45
	v_exp_f32_e32 v48, v42
	s_waitcnt lgkmcnt(1)
	v_cndmask_b32_e64 v75, v46, v54, s[40:41]
	v_mov_b32_e32 v42, v38
	v_mov_b32_e32 v43, v78
	s_waitcnt lgkmcnt(0)
	v_cndmask_b32_e64 v46, v56, v47, s[42:43]
	v_fma_f32 v46, v66, v46, v70
	v_fma_f32 v43, v43, v75, v46
	v_fma_f32 v42, v42, v74, v43
	v_mul_f32_e32 v43, 0xbfb8aa3b, v42
	v_exp_f32_e32 v43, v43
	v_add_f32_e32 v46, 1.0, v48
	v_rcp_f32_e32 v46, v46
	v_mul_f32_e32 v44, v50, v44
	v_add_f32_e32 v43, 1.0, v43
	v_rcp_f32_e32 v43, v43
	v_pk_mul_f32 v[34:35], v[34:35], v[134:135]
	v_mul_f32_e32 v36, v36, v44
	v_mul_f32_e32 v44, v45, v46
	v_mul_f32_e32 v42, v42, v43
	v_mul_f32_e32 v35, v35, v44
	v_mul_f32_e32 v34, v34, v42
	v_cvt_pk_bf16_f32 v34, v34, v35
	v_cvt_pk_bf16_f32 v35, v36, v37
	s_nop 1
	v_permlane16_swap_b32_e32 v210, v34
	v_permlane16_swap_b32_e32 v211, v35
	v_mov_b32_e32 v220, v210
	v_mov_b32_e32 v221, v211
	v_mov_b32_e32 v222, v34
	v_mov_b32_e32 v223, v35
	v_add_co_u32_e64 v110, s[98:99], v110, v205
	s_nop 1
	v_addc_co_u32_e64 v111, s[98:99], 0, v111, s[98:99]
	global_store_dwordx4 v[110:111], v[220:223], off nt
	s_and_saveexec_b64 s[10:11], s[44:45]
	s_cbranch_execz .LBB0_59
	global_store_dwordx4 v[106:107], v[38:41], off offset:64
.LBB0_59:
	s_or_b64 exec, exec, s[10:11]
	v_mov_b32_e32 v103, v102
	v_mov_b32_e32 v42, v102
	v_mov_b32_e32 v43, v102
	v_pk_mul_f32 v[36:37], v[28:29], v[42:43]
	v_pk_mul_f32 v[34:35], v[26:27], v[102:103]
	s_nop 1
	v_mov_b32_dpp v75, v34 row_ror:1 row_mask:0xf bank_mask:0xf
	v_mov_b32_dpp v38, v34 row_ror:2 row_mask:0xf bank_mask:0xf
	v_mov_b32_dpp v63, v35 row_ror:1 row_mask:0xf bank_mask:0xf
	v_mov_b32_dpp v39, v35 row_ror:2 row_mask:0xf bank_mask:0xf
	v_mov_b32_dpp v77, v36 row_ror:1 row_mask:0xf bank_mask:0xf
	v_mov_b32_dpp v40, v36 row_ror:2 row_mask:0xf bank_mask:0xf
	v_mov_b32_dpp v65, v37 row_ror:1 row_mask:0xf bank_mask:0xf
	v_mov_b32_dpp v41, v37 row_ror:2 row_mask:0xf bank_mask:0xf
	v_pk_mul_f32 v[28:29], v[32:33], v[42:43]
	v_pk_mul_f32 v[26:27], v[30:31], v[102:103]
	s_and_saveexec_b64 s[10:11], s[42:43]
	s_xor_b64 s[10:11], exec, s[10:11]
	s_cbranch_execz .LBB0_61
	v_mov_b32_e32 v30, v37
	v_mov_b32_e32 v31, v81
	s_waitcnt lgkmcnt(1)
	s_waitcnt lgkmcnt(0)
	v_fma_f32 v32, v69, v41, v73
	v_fma_f32 v31, v31, v65, v32
	v_fma_f32 v30, v30, v64, v31
	v_mul_f32_e32 v31, 0xbfb8aa3b, v30
	v_exp_f32_e32 v31, v31
	v_mov_b32_e32 v37, v80
	v_add_f32_e32 v31, 1.0, v31
	v_rcp_f32_e32 v31, v31
	s_nop 0
	v_mul_f32_e32 v30, v30, v31
	v_mul_f32_e32 v32, v29, v30
	v_fma_f32 v29, v68, v40, v72
	v_fma_f32 v29, v37, v77, v29
	v_fma_f32 v29, v36, v76, v29
	v_mul_f32_e32 v30, 0xbfb8aa3b, v29
	v_exp_f32_e32 v30, v30
	v_fma_f32 v31, v67, v39, v71
	v_add_f32_e32 v30, 1.0, v30
	v_rcp_f32_e32 v30, v30
	s_nop 0
	v_mul_f32_e32 v29, v29, v30
	v_mul_f32_e32 v30, v28, v29
	v_mov_b32_e32 v28, v35
	v_mov_b32_e32 v29, v79
	v_mov_b32_e32 v35, v78
	v_fma_f32 v29, v29, v63, v31
	v_fma_f32 v28, v28, v62, v29
	v_mul_f32_e32 v29, 0xbfb8aa3b, v28
	v_exp_f32_e32 v29, v29
	v_fma_f32 v31, v66, v38, v70
	v_add_f32_e32 v29, 1.0, v29
	v_rcp_f32_e32 v29, v29
	s_nop 0
	v_mul_f32_e32 v28, v28, v29
	v_mul_f32_e32 v27, v27, v28
	s_nop 0
	v_fma_f32 v29, v35, v75, v31
	v_fma_f32 v28, v34, v74, v29
	v_mul_f32_e32 v29, 0xbfb8aa3b, v28
	v_exp_f32_e32 v29, v29
	s_nop 0
	v_add_f32_e32 v29, 1.0, v29
	v_rcp_f32_e32 v29, v29
	s_nop 0
	v_mul_f32_e32 v28, v28, v29
	v_mul_f32_e32 v26, v26, v28
	v_mov_b64_e32 v[28:29], s[48:49]
	v_mad_i64_i32 v[28:29], s[12:13], v180, s17, v[28:29]
	v_cvt_pk_bf16_f32 v26, v26, v27
	v_cvt_pk_bf16_f32 v27, v30, v32
	v_lshl_add_u64 v[28:29], v[156:157], 1, v[28:29]
	s_nop 1
	v_permlane16_swap_b32_e32 v212, v26
	v_permlane16_swap_b32_e32 v213, v27
	v_mov_b32_e32 v220, v212
	v_mov_b32_e32 v221, v213
	v_mov_b32_e32 v222, v26
	v_mov_b32_e32 v223, v27
	v_add_co_u32_e64 v28, s[98:99], v28, v205
	s_nop 1
	v_addc_co_u32_e64 v29, s[98:99], 0, v29, s[98:99]
	global_store_dwordx4 v[28:29], v[220:223], off nt

;     __device__ __forceinline__ void operator()(const f32x4 (&acc)[2][2][4][2], const Unit& u, int wr, int wc, int fr, int fq) const {
;     ...
;             for (int m = 0; m < 4; ++m) rs[ai][m] = __builtin_amdgcn_rsqf((float)ss[u.pm * BM + ai * HALF + wr * 64 + m * 16 + fr] * (1.f / (2048.f * 262144.f)) + 1e-6f);
; #pragma unroll
;         for (int n = 0; n < 2; ++n) {
;             const int cbase = 128 * u.pn + 32 * wc + 16 * n + 4 * fq;
;             const f32x4 w0 = *(const f32x4*)(cw + cbase), w1 = *(const f32x4*)(cw + FF + cbase), w2 = *(const f32x4*)(cw + 2 * FF + cbase), b4 = *(const f32x4*)(cb + cbase);
; #pragma unroll
;             for (int ai = 0; ai < 2; ++ai) {
;                 const int slab = u.pm * 4 + 2 * ai + wr;
;                 f32x4 r1p = (f32x4){0.f, 0.f, 0.f, 0.f}, r2p = (f32x4){0.f, 0.f, 0.f, 0.f};
; #pragma unroll
;                 for (int m = 0; m < 4; ++m) {
;                     const f32x4 g = acc[ai][1][m][n] * rs[ai][m], v = acc[ai][0][m][n] * rs[ai][m];
;                     f32x4 r1, r2, a;
; #pragma unroll
;                     for (int e = 0; e < 4; ++e) { r1[e] = __shfl(g[e], src1); r2[e] = __shfl(g[e], src2); }
; #pragma unroll
;                     for (int e = 0; e < 4; ++e) {
;                         const float p1 = fr >= 1 ? r1[e] : r1p[e], p2 = fr >= 2 ? r2[e] : r2p[e];
;                         const float gg = b4[e] + w0[e] * p2 + w1[e] * p1 + w2[e] * g[e];
;                         a[e] = gg * __builtin_amdgcn_rcpf(1.f + __expf(-gg)) * v[e];
;                     }
;                     r1p = r1; r2p = r2;
;                     const size_t row = (size_t)(u.pm * BM + ai * HALF + wr * 64 + m * 16 + fr);
;                     if (m == 0 && fr < 2) {
;                         *(f32x4*)(GF + (size_t)(slab * 2 + fr) * FF + cbase) = g; *(f32x4*)(VF + (size_t)(slab * 2 + fr) * FF + cbase) = v;
;                     } else {
;                         typedef unsigned u32x2v __attribute__((ext_vector_type(2)));
;                         u32x2v w; w.x = cvt_pk_bf16(a[0], a[1]); w.y = cvt_pk_bf16(a[2], a[3]);
;                         *(u32x2v*)(ACT + row * FF + cbase) = w;
;                     }
;                     if (m == 3 && fr >= 14) *(f32x4*)(GL + (size_t)(slab * 2 + fr - 14) * FF + cbase) = g;
.LBB0_63:
	s_or_b64 exec, exec, s[10:11]
	s_nop 0
	v_mov_b32_e32 v26, v94
	v_mov_b32_e32 v27, v94
	v_pk_mul_f32 v[24:25], v[24:25], v[26:27]
	s_nop 1
	v_mov_b32_dpp v31, v25 row_ror:1 row_mask:0xf bank_mask:0xf
	v_mov_b32_dpp v35, v25 row_ror:2 row_mask:0xf bank_mask:0xf
	v_mov_b32_e32 v28, v25
	v_mov_b32_e32 v29, v81
	v_mov_b32_dpp v36, v24 row_ror:2 row_mask:0xf bank_mask:0xf
	s_waitcnt lgkmcnt(2)
	v_cndmask_b32_e64 v65, v31, v65, s[40:41]
	s_waitcnt lgkmcnt(1)
	v_cndmask_b32_e64 v25, v41, v35, s[42:43]
	v_fma_f32 v25, v69, v25, v73
	v_fma_f32 v25, v29, v65, v25
	v_fma_f32 v28, v28, v64, v25
	v_mul_f32_e32 v25, 0xbfb8aa3b, v28
	v_exp_f32_e32 v25, v25
	v_mov_b32_dpp v29, v24 row_ror:1 row_mask:0xf bank_mask:0xf
	v_pk_mul_f32 v[20:21], v[20:21], v[26:27]
	s_waitcnt lgkmcnt(1)
	v_cndmask_b32_e64 v27, v40, v36, s[42:43]
	v_add_f32_e32 v25, 1.0, v25
	v_rcp_f32_e32 v26, v25
	s_waitcnt lgkmcnt(0)
	v_cndmask_b32_e64 v77, v29, v77, s[40:41]
	v_mov_b32_e32 v25, v80
	v_fma_f32 v27, v68, v27, v72
	v_fma_f32 v25, v25, v77, v27
	v_mov_b32_e32 v95, v94
	v_fma_f32 v27, v24, v76, v25
	v_pk_mul_f32 v[22:23], v[22:23], v[94:95]
	v_mul_f32_e32 v24, 0xbfb8aa3b, v27
	s_nop 1
	v_mov_b32_dpp v33, v23 row_ror:1 row_mask:0xf bank_mask:0xf
	v_mov_b32_dpp v34, v23 row_ror:2 row_mask:0xf bank_mask:0xf
	v_exp_f32_e32 v24, v24
	v_mul_f32_e32 v25, v28, v26
	v_mov_b32_dpp v30, v22 row_ror:1 row_mask:0xf bank_mask:0xf
	v_mov_b32_dpp v32, v22 row_ror:2 row_mask:0xf bank_mask:0xf
	v_add_f32_e32 v24, 1.0, v24
	v_mul_f32_e32 v21, v21, v25
	v_rcp_f32_e32 v26, v24
	s_waitcnt lgkmcnt(3)
	v_cndmask_b32_e64 v63, v33, v63, s[40:41]
	v_mov_b32_e32 v24, v23
	v_mov_b32_e32 v25, v79
	s_waitcnt lgkmcnt(2)
	v_cndmask_b32_e64 v23, v39, v34, s[42:43]
	v_fma_f32 v23, v67, v23, v71
	v_fma_f32 v23, v25, v63, v23
	v_fma_f32 v24, v24, v62, v23
	v_mul_f32_e32 v23, 0xbfb8aa3b, v24
	v_exp_f32_e32 v25, v23
	s_waitcnt lgkmcnt(1)
	v_cndmask_b32_e64 v75, v30, v75, s[40:41]
	v_mov_b32_e32 v23, v78
	s_waitcnt lgkmcnt(0)
	v_cndmask_b32_e64 v28, v38, v32, s[42:43]
	v_fma_f32 v28, v66, v28, v70
	v_fma_f32 v23, v23, v75, v28
	v_fma_f32 v22, v22, v74, v23
	v_mul_f32_e32 v23, 0xbfb8aa3b, v22
	v_exp_f32_e32 v23, v23
	v_add_f32_e32 v25, 1.0, v25
	v_rcp_f32_e32 v25, v25
	v_pk_mul_f32 v[18:19], v[18:19], v[94:95]
	v_add_f32_e32 v23, 1.0, v23
	v_rcp_f32_e32 v23, v23
	v_mul_f32_e32 v24, v24, v25
	v_mul_f32_e32 v26, v27, v26
	v_mul_f32_e32 v19, v19, v24
	v_mul_f32_e32 v22, v22, v23
	v_mul_f32_e32 v18, v18, v22
	v_mul_f32_e32 v20, v20, v26
	v_cvt_pk_bf16_f32 v18, v18, v19
	v_cvt_pk_bf16_f32 v19, v20, v21
	s_nop 1
	v_permlane16_swap_b32_e32 v214, v18
	v_permlane16_swap_b32_e32 v215, v19
	v_mov_b32_e32 v220, v214
	v_mov_b32_e32 v221, v215
	v_mov_b32_e32 v222, v18
	v_mov_b32_e32 v223, v19
	v_add_co_u32_e64 v98, s[98:99], v98, v205
	s_nop 1
	v_addc_co_u32_e64 v99, s[98:99], 0, v99, s[98:99]
	global_store_dwordx4 v[98:99], v[220:223], off nt
	v_mov_b32_e32 v18, v92
	v_mov_b32_e32 v19, v92
	v_pk_mul_f32 v[16:17], v[16:17], v[18:19]
	s_nop 1
	v_mov_b32_dpp v23, v17 row_ror:1 row_mask:0xf bank_mask:0xf
	v_mov_b32_dpp v27, v17 row_ror:2 row_mask:0xf bank_mask:0xf
	v_mov_b32_e32 v20, v17
	v_mov_b32_e32 v21, v81
	v_mov_b32_dpp v28, v16 row_ror:2 row_mask:0xf bank_mask:0xf
	s_waitcnt lgkmcnt(2)
	v_cndmask_b32_e64 v65, v23, v31, s[40:41]
	s_waitcnt lgkmcnt(1)
	v_cndmask_b32_e64 v17, v35, v27, s[42:43]
	v_fma_f32 v17, v69, v17, v73
	v_fma_f32 v17, v21, v65, v17
	v_fma_f32 v20, v20, v64, v17
	v_mul_f32_e32 v17, 0xbfb8aa3b, v20
	v_exp_f32_e32 v17, v17
	v_mov_b32_dpp v21, v16 row_ror:1 row_mask:0xf bank_mask:0xf
	v_pk_mul_f32 v[12:13], v[12:13], v[18:19]
	s_waitcnt lgkmcnt(1)
	v_cndmask_b32_e64 v19, v36, v28, s[42:43]
	v_add_f32_e32 v17, 1.0, v17
	v_rcp_f32_e32 v18, v17
	s_waitcnt lgkmcnt(0)
	v_cndmask_b32_e64 v77, v21, v29, s[40:41]
	v_mov_b32_e32 v17, v80
	v_fma_f32 v19, v68, v19, v72
	v_fma_f32 v17, v17, v77, v19
	v_mov_b32_e32 v93, v92
	v_fma_f32 v19, v16, v76, v17
	v_pk_mul_f32 v[14:15], v[14:15], v[92:93]
	v_mul_f32_e32 v16, 0xbfb8aa3b, v19
	s_nop 1
	v_mov_b32_dpp v25, v15 row_ror:1 row_mask:0xf bank_mask:0xf
	v_mov_b32_dpp v26, v15 row_ror:2 row_mask:0xf bank_mask:0xf
	v_exp_f32_e32 v16, v16
	v_mul_f32_e32 v17, v20, v18
	v_mov_b32_dpp v22, v14 row_ror:1 row_mask:0xf bank_mask:0xf
	v_mov_b32_dpp v24, v14 row_ror:2 row_mask:0xf bank_mask:0xf
	v_add_f32_e32 v16, 1.0, v16
	v_mul_f32_e32 v13, v13, v17
	v_rcp_f32_e32 v18, v16
	s_waitcnt lgkmcnt(3)
;     __device__ __forceinline__ void operator()(const f32x4 (&acc)[2][2][4][2], const Unit& u, int wr, int wc, int fr, int fq) const {
;     ...
;             for (int m = 0; m < 4; ++m) rs[ai][m] = __builtin_amdgcn_rsqf((float)ss[u.pm * BM + ai * HALF + wr * 64 + m * 16 + fr] * (1.f / (2048.f * 262144.f)) + 1e-6f);
; #pragma unroll
;         for (int n = 0; n < 2; ++n) {
;             const int cbase = 128 * u.pn + 32 * wc + 16 * n + 4 * fq;
;             const f32x4 w0 = *(const f32x4*)(cw + cbase), w1 = *(const f32x4*)(cw + FF + cbase), w2 = *(const f32x4*)(cw + 2 * FF + cbase), b4 = *(const f32x4*)(cb + cbase);
; #pragma unroll
;             for (int ai = 0; ai < 2; ++ai) {
;                 const int slab = u.pm * 4 + 2 * ai + wr;
;                 f32x4 r1p = (f32x4){0.f, 0.f, 0.f, 0.f}, r2p = (f32x4){0.f, 0.f, 0.f, 0.f};
; #pragma unroll
;                 for (int m = 0; m < 4; ++m) {
;                     const f32x4 g = acc[ai][1][m][n] * rs[ai][m], v = acc[ai][0][m][n] * rs[ai][m];
;                     f32x4 r1, r2, a;
; #pragma unroll
;                     for (int e = 0; e < 4; ++e) { r1[e] = __shfl(g[e], src1); r2[e] = __shfl(g[e], src2); }
; #pragma unroll
;                     for (int e = 0; e < 4; ++e) {
;                         const float p1 = fr >= 1 ? r1[e] : r1p[e], p2 = fr >= 2 ? r2[e] : r2p[e];
;                         const float gg = b4[e] + w0[e] * p2 + w1[e] * p1 + w2[e] * g[e];
;                         a[e] = gg * __builtin_amdgcn_rcpf(1.f + __expf(-gg)) * v[e];
;                     }
;                     r1p = r1; r2p = r2;
;                     const size_t row = (size_t)(u.pm * BM + ai * HALF + wr * 64 + m * 16 + fr);
;                     if (m == 0 && fr < 2) {
;                         *(f32x4*)(GF + (size_t)(slab * 2 + fr) * FF + cbase) = g; *(f32x4*)(VF + (size_t)(slab * 2 + fr) * FF + cbase) = v;
;                     } else {
;                         typedef unsigned u32x2v __attribute__((ext_vector_type(2)));
;                         u32x2v w; w.x = cvt_pk_bf16(a[0], a[1]); w.y = cvt_pk_bf16(a[2], a[3]);
;                         *(u32x2v*)(ACT + row * FF + cbase) = w;
;                     }
;                     if (m == 3 && fr >= 14) *(f32x4*)(GL + (size_t)(slab * 2 + fr - 14) * FF + cbase) = g;
	v_cndmask_b32_e64 v63, v25, v33, s[40:41]
	v_mov_b32_e32 v16, v15
	v_mov_b32_e32 v17, v79
	s_waitcnt lgkmcnt(2)
	v_cndmask_b32_e64 v15, v34, v26, s[42:43]
	v_fma_f32 v15, v67, v15, v71
	v_fma_f32 v15, v17, v63, v15
	v_fma_f32 v16, v16, v62, v15
	v_mul_f32_e32 v15, 0xbfb8aa3b, v16
	v_exp_f32_e32 v17, v15
	s_waitcnt lgkmcnt(1)
	v_cndmask_b32_e64 v75, v22, v30, s[40:41]
	v_mov_b32_e32 v15, v78
	s_waitcnt lgkmcnt(0)
	v_cndmask_b32_e64 v20, v32, v24, s[42:43]
	v_fma_f32 v20, v66, v20, v70
	v_fma_f32 v15, v15, v75, v20
	v_fma_f32 v14, v14, v74, v15
	v_mul_f32_e32 v15, 0xbfb8aa3b, v14
	v_exp_f32_e32 v15, v15
	v_add_f32_e32 v17, 1.0, v17
	v_rcp_f32_e32 v17, v17
	v_pk_mul_f32 v[10:11], v[10:11], v[92:93]
	v_add_f32_e32 v15, 1.0, v15
	v_rcp_f32_e32 v15, v15
	v_mul_f32_e32 v16, v16, v17
	v_mul_f32_e32 v18, v19, v18
	v_mul_f32_e32 v11, v11, v16
	v_mul_f32_e32 v14, v14, v15
	v_mul_f32_e32 v10, v10, v14
	v_mul_f32_e32 v12, v12, v18
	v_cvt_pk_bf16_f32 v10, v10, v11
	v_cvt_pk_bf16_f32 v11, v12, v13
	s_nop 1
	v_permlane16_swap_b32_e32 v216, v10
	v_permlane16_swap_b32_e32 v217, v11
	v_mov_b32_e32 v220, v216
	v_mov_b32_e32 v221, v217
	v_mov_b32_e32 v222, v10
	v_mov_b32_e32 v223, v11
	v_add_co_u32_e64 v96, s[98:99], v96, v205
	s_nop 1
	v_addc_co_u32_e64 v97, s[98:99], 0, v97, s[98:99]
	global_store_dwordx4 v[96:97], v[220:223], off nt
	v_mov_b32_e32 v10, v90
	v_mov_b32_e32 v11, v90
	v_pk_mul_f32 v[8:9], v[8:9], v[10:11]
	s_nop 1
	v_mov_b32_dpp v12, v9 row_ror:1 row_mask:0xf bank_mask:0xf
	v_mov_b32_dpp v18, v9 row_ror:2 row_mask:0xf bank_mask:0xf
	v_mov_b32_e32 v13, v81
	v_mov_b32_dpp v19, v8 row_ror:2 row_mask:0xf bank_mask:0xf
	v_pk_mul_f32 v[4:5], v[4:5], v[10:11]
	s_waitcnt lgkmcnt(2)
	v_cndmask_b32_e64 v65, v12, v23, s[40:41]
	v_mov_b32_e32 v12, v9
	s_waitcnt lgkmcnt(1)
	v_cndmask_b32_e64 v18, v27, v18, s[42:43]
	v_fma_f32 v18, v69, v18, v73
	v_fma_f32 v13, v13, v65, v18
	v_fma_f32 v12, v12, v64, v13
	v_mul_f32_e32 v13, 0xbfb8aa3b, v12
	v_exp_f32_e32 v13, v13
	v_mov_b32_dpp v18, v8 row_ror:1 row_mask:0xf bank_mask:0xf
	v_mov_b32_e32 v11, v80
	v_mov_b32_e32 v91, v90
	v_add_f32_e32 v10, 1.0, v13
	v_rcp_f32_e32 v13, v10
	s_waitcnt lgkmcnt(0)
	v_cndmask_b32_e64 v77, v18, v21, s[40:41]
	v_mov_b32_e32 v10, v8
	v_cndmask_b32_e64 v18, v28, v19, s[42:43]
	v_fma_f32 v18, v68, v18, v72
	v_fma_f32 v11, v11, v77, v18
	v_fma_f32 v18, v10, v76, v11
	v_pk_mul_f32 v[6:7], v[6:7], v[90:91]
	v_mul_f32_e32 v10, 0xbfb8aa3b, v18
	s_nop 1
	v_mov_b32_dpp v16, v7 row_ror:1 row_mask:0xf bank_mask:0xf
	v_mov_b32_dpp v17, v7 row_ror:2 row_mask:0xf bank_mask:0xf
	v_exp_f32_e32 v10, v10
	v_mul_f32_e32 v11, v12, v13
	v_mov_b32_dpp v14, v6 row_ror:1 row_mask:0xf bank_mask:0xf
	v_mov_b32_dpp v15, v6 row_ror:2 row_mask:0xf bank_mask:0xf
	v_add_f32_e32 v10, 1.0, v10
	v_mul_f32_e32 v5, v5, v11
	v_rcp_f32_e32 v12, v10
	s_waitcnt lgkmcnt(3)
	v_cndmask_b32_e64 v63, v16, v25, s[40:41]
	v_mov_b32_e32 v10, v7
	v_mov_b32_e32 v11, v79
	s_waitcnt lgkmcnt(2)
	v_cndmask_b32_e64 v13, v26, v17, s[42:43]
	v_fma_f32 v13, v67, v13, v71
	v_fma_f32 v11, v11, v63, v13
	v_fma_f32 v13, v10, v62, v11
	v_mul_f32_e32 v10, 0xbfb8aa3b, v13
	v_exp_f32_e32 v16, v10
	s_waitcnt lgkmcnt(1)
	v_cndmask_b32_e64 v75, v14, v22, s[40:41]
	v_mov_b32_e32 v10, v6
	v_mov_b32_e32 v11, v78
	s_waitcnt lgkmcnt(0)
	v_cndmask_b32_e64 v14, v24, v15, s[42:43]
	v_fmac_f32_e32 v70, v66, v14
	v_fma_f32 v11, v11, v75, v70
	v_fma_f32 v10, v10, v74, v11
	v_mul_f32_e32 v11, 0xbfb8aa3b, v10
	v_exp_f32_e32 v11, v11
	v_add_f32_e32 v14, 1.0, v16
	v_rcp_f32_e32 v14, v14
	v_mul_f32_e32 v12, v18, v12
	v_add_f32_e32 v11, 1.0, v11
	v_rcp_f32_e32 v11, v11
	v_pk_mul_f32 v[2:3], v[2:3], v[90:91]
	v_mul_f32_e32 v4, v4, v12
	v_mul_f32_e32 v12, v13, v14
	v_mul_f32_e32 v10, v10, v11
	v_mul_f32_e32 v3, v3, v12
	v_mul_f32_e32 v2, v2, v10
	v_cvt_pk_bf16_f32 v2, v2, v3
	v_cvt_pk_bf16_f32 v3, v4, v5
	s_nop 1
	v_permlane16_swap_b32_e32 v218, v2
	v_permlane16_swap_b32_e32 v219, v3
	v_mov_b32_e32 v220, v218
	v_mov_b32_e32 v221, v219
	v_mov_b32_e32 v222, v2
	v_mov_b32_e32 v223, v3
	v_add_co_u32_e64 v88, s[98:99], v88, v205
	s_nop 1
	v_addc_co_u32_e64 v89, s[98:99], 0, v89, s[98:99]
	global_store_dwordx4 v[88:89], v[220:223], off nt
	s_and_saveexec_b64 s[10:11], s[44:45]
	s_cbranch_execz .LBB0_65
	global_store_dwordx4 v[86:87], v[6:9], off offset:64
